# GEMM K-loops: setprio raised before the barrier so an MFMA issues first after release; dropped redundant lgkmcnt wait and mid-block setprio flips
# speedup vs baseline: 1.0001x; 1.0001x over previous
.LBB0_230:
	s_add_u32 s33, s38, 0xfff00080
	s_addc_u32 s73, s39, -1
	s_add_i32 s75, 0, 0x10000
	s_cmp_eq_u32 s19, 60
	s_cselect_b32 s87, s1, s73
	s_cselect_b32 s86, s14, s33
	v_add_u32_e32 v114, s75, v119
	s_cselect_b32 s85, s15, s18
	s_cselect_b32 s84, s16, s17
	s_add_i32 s33, 0, 0x14000
	ds_read_b128 v[160:163], v114
	ds_read_b128 v[164:167], v114 offset:1024
	ds_read_b128 v[168:171], v114 offset:2048
	ds_read_b128 v[172:175], v114 offset:3072
	v_add_u32_e32 v114, s33, v119
	ds_read_b128 v[176:179], v114
	ds_read_b128 v[180:183], v114 offset:1024
	ds_read_b128 v[184:187], v114 offset:2048
	ds_read_b128 v[188:191], v114 offset:3072
	v_lshl_add_u64 v[202:203], s[38:39], 0, v[156:157]
	s_add_i32 m0, s7, 0xc000
	ds_read_b128 v[192:195], v141
	ds_read_b128 v[196:199], v141 offset:1024
	ds_read_b128 v[210:213], v141 offset:2048
	ds_read_b128 v[214:217], v141 offset:3072
	ds_read_b128 v[218:221], v141 offset:4096
	ds_read_b128 v[222:225], v141 offset:5120
	ds_read_b128 v[226:229], v141 offset:6144
	ds_read_b128 v[236:239], v141 offset:7168
	global_load_lds_dwordx4 v[202:203], off
	v_lshl_add_u64 v[202:203], s[38:39], 0, v[158:159]
	s_add_i32 m0, s7, 0xe000
	s_nop 0
	global_load_lds_dwordx4 v[202:203], off
	s_waitcnt vmcnt(8)
	s_waitcnt lgkmcnt(0)
	s_setprio 1
	s_barrier
	v_mfma_f32_16x16x32_bf16 v[132:135], v[160:163], v[192:195], v[132:135]
	v_mfma_f32_16x16x32_bf16 v[128:131], v[168:171], v[192:195], v[128:131]
	v_mfma_f32_16x16x32_bf16 v[124:127], v[160:163], v[210:213], v[124:127]
	v_mfma_f32_16x16x32_bf16 v[110:113], v[168:171], v[210:213], v[110:113]
	v_mfma_f32_16x16x32_bf16 v[102:105], v[160:163], v[218:221], v[102:105]
	v_mfma_f32_16x16x32_bf16 v[94:97], v[168:171], v[218:221], v[94:97]
	v_mfma_f32_16x16x32_bf16 v[86:89], v[160:163], v[226:229], v[86:89]
	v_mfma_f32_16x16x32_bf16 v[78:81], v[168:171], v[226:229], v[78:81]
	v_mfma_f32_16x16x32_bf16 v[132:135], v[164:167], v[196:199], v[132:135]
	v_mfma_f32_16x16x32_bf16 v[128:131], v[172:175], v[196:199], v[128:131]
	v_mfma_f32_16x16x32_bf16 v[124:127], v[164:167], v[214:217], v[124:127]
	v_mfma_f32_16x16x32_bf16 v[110:113], v[172:175], v[214:217], v[110:113]
	v_mfma_f32_16x16x32_bf16 v[102:105], v[164:167], v[222:225], v[102:105]
	v_mfma_f32_16x16x32_bf16 v[94:97], v[172:175], v[222:225], v[94:97]
	v_mfma_f32_16x16x32_bf16 v[86:89], v[164:167], v[236:239], v[86:89]
	v_mfma_f32_16x16x32_bf16 v[78:81], v[172:175], v[236:239], v[78:81]
	v_mfma_f32_16x16x32_bf16 v[120:123], v[176:179], v[192:195], v[120:123]
	v_mfma_f32_16x16x32_bf16 v[106:109], v[184:187], v[192:195], v[106:109]
	v_mfma_f32_16x16x32_bf16 v[98:101], v[176:179], v[210:213], v[98:101]
	v_mfma_f32_16x16x32_bf16 v[90:93], v[184:187], v[210:213], v[90:93]
	v_mfma_f32_16x16x32_bf16 v[82:85], v[176:179], v[218:221], v[82:85]
	v_mfma_f32_16x16x32_bf16 v[74:77], v[184:187], v[218:221], v[74:77]
	v_mfma_f32_16x16x32_bf16 v[70:73], v[176:179], v[226:229], v[70:73]
	v_mfma_f32_16x16x32_bf16 v[66:69], v[184:187], v[226:229], v[66:69]
	v_mfma_f32_16x16x32_bf16 v[120:123], v[180:183], v[196:199], v[120:123]
	v_mfma_f32_16x16x32_bf16 v[106:109], v[188:191], v[196:199], v[106:109]
	v_mfma_f32_16x16x32_bf16 v[98:101], v[180:183], v[214:217], v[98:101]
	v_mfma_f32_16x16x32_bf16 v[90:93], v[188:191], v[214:217], v[90:93]
	v_mfma_f32_16x16x32_bf16 v[82:85], v[180:183], v[222:225], v[82:85]
	v_mfma_f32_16x16x32_bf16 v[74:77], v[188:191], v[222:225], v[74:77]
	v_mfma_f32_16x16x32_bf16 v[70:73], v[180:183], v[236:239], v[70:73]
	v_mfma_f32_16x16x32_bf16 v[66:69], v[188:191], v[236:239], v[66:69]
	s_barrier
	s_setprio 0
	s_add_i32 s73, s75, s6
	v_lshl_add_u64 v[202:203], s[84:85], 0, v[148:149]
	s_mov_b32 m0, s73
	ds_read_b128 v[192:195], v141 offset:16384
	ds_read_b128 v[196:199], v141 offset:17408
	ds_read_b128 v[210:213], v141 offset:18432
	ds_read_b128 v[214:217], v141 offset:19456
	ds_read_b128 v[218:221], v141 offset:20480
	ds_read_b128 v[222:225], v141 offset:21504
	ds_read_b128 v[226:229], v141 offset:22528
	ds_read_b128 v[236:239], v141 offset:23552
	global_load_lds_dwordx4 v[202:203], off
	s_add_i32 m0, s73, 0x2000
	s_add_u32 vcc_lo, s84, 0x100000
	v_lshl_add_u64 v[240:241], s[84:85], 0, v[152:153]
	s_addc_u32 vcc_hi, s85, 0
	s_add_i32 s33, s33, s6
	global_load_lds_dwordx4 v[240:241], off
	v_lshl_add_u64 v[242:243], vcc, 0, v[148:149]
	s_mov_b32 m0, s33
	v_lshl_add_u64 v[244:245], s[86:87], 0, v[150:151]
	global_load_lds_dwordx4 v[242:243], off
	v_lshl_add_u64 v[242:243], vcc, 0, v[152:153]
	s_add_i32 m0, s33, 0x2000
	s_nop 0
	global_load_lds_dwordx4 v[242:243], off
	v_lshl_add_u64 v[242:243], s[86:87], 0, v[146:147]
	s_mov_b32 m0, s7
	s_nop 0
	global_load_lds_dwordx4 v[242:243], off
	s_mov_b32 m0, s8
	s_nop 0
	global_load_lds_dwordx4 v[244:245], off
	s_waitcnt vmcnt(8)
	s_waitcnt lgkmcnt(0)
	s_setprio 1
	s_barrier
	v_mfma_f32_16x16x32_bf16 v[62:65], v[160:163], v[192:195], v[62:65]
	v_mfma_f32_16x16x32_bf16 v[58:61], v[168:171], v[192:195], v[58:61]
	v_mfma_f32_16x16x32_bf16 v[54:57], v[160:163], v[210:213], v[54:57]
	v_mfma_f32_16x16x32_bf16 v[46:49], v[168:171], v[210:213], v[46:49]
	v_mfma_f32_16x16x32_bf16 v[38:41], v[160:163], v[218:221], v[38:41]
	v_mfma_f32_16x16x32_bf16 v[30:33], v[168:171], v[218:221], v[30:33]
	v_mfma_f32_16x16x32_bf16 v[22:25], v[160:163], v[226:229], v[22:25]
	v_mfma_f32_16x16x32_bf16 v[14:17], v[168:171], v[226:229], v[14:17]
	v_mfma_f32_16x16x32_bf16 v[62:65], v[164:167], v[196:199], v[62:65]
	v_mfma_f32_16x16x32_bf16 v[58:61], v[172:175], v[196:199], v[58:61]
	v_mfma_f32_16x16x32_bf16 v[54:57], v[164:167], v[214:217], v[54:57]
	v_mfma_f32_16x16x32_bf16 v[46:49], v[172:175], v[214:217], v[46:49]
	v_mfma_f32_16x16x32_bf16 v[38:41], v[164:167], v[222:225], v[38:41]
	v_mfma_f32_16x16x32_bf16 v[30:33], v[172:175], v[222:225], v[30:33]
	v_mfma_f32_16x16x32_bf16 v[22:25], v[164:167], v[236:239], v[22:25]
	v_mfma_f32_16x16x32_bf16 v[14:17], v[172:175], v[236:239], v[14:17]
	v_mfma_f32_16x16x32_bf16 v[50:53], v[176:179], v[192:195], v[50:53]
	v_mfma_f32_16x16x32_bf16 v[42:45], v[184:187], v[192:195], v[42:45]
	v_mfma_f32_16x16x32_bf16 v[34:37], v[176:179], v[210:213], v[34:37]
	v_mfma_f32_16x16x32_bf16 v[26:29], v[184:187], v[210:213], v[26:29]
	v_mfma_f32_16x16x32_bf16 v[18:21], v[176:179], v[218:221], v[18:21]
	v_mfma_f32_16x16x32_bf16 v[10:13], v[184:187], v[218:221], v[10:13]
	v_mfma_f32_16x16x32_bf16 v[6:9], v[176:179], v[226:229], v[6:9]
	v_mfma_f32_16x16x32_bf16 v[2:5], v[184:187], v[226:229], v[2:5]
	v_mfma_f32_16x16x32_bf16 v[50:53], v[180:183], v[196:199], v[50:53]
	v_mfma_f32_16x16x32_bf16 v[42:45], v[188:191], v[196:199], v[42:45]
	v_mfma_f32_16x16x32_bf16 v[34:37], v[180:183], v[214:217], v[34:37]
	v_mfma_f32_16x16x32_bf16 v[26:29], v[188:191], v[214:217], v[26:29]
	v_mfma_f32_16x16x32_bf16 v[18:21], v[180:183], v[222:225], v[18:21]
	v_mfma_f32_16x16x32_bf16 v[10:13], v[188:191], v[222:225], v[10:13]
	v_mfma_f32_16x16x32_bf16 v[6:9], v[180:183], v[236:239], v[6:9]
	v_mfma_f32_16x16x32_bf16 v[2:5], v[188:191], v[236:239], v[2:5]
	s_barrier
	s_setprio 0
	s_add_i32 s33, 0, 0x18000
	v_add_u32_e32 v114, s33, v119
	s_add_i32 s73, 0, 0x1c000
	ds_read_b128 v[160:163], v114
	ds_read_b128 v[164:167], v114 offset:1024
	ds_read_b128 v[168:171], v114 offset:2048
	ds_read_b128 v[172:175], v114 offset:3072
	v_add_u32_e32 v114, s73, v119
	ds_read_b128 v[176:179], v114
	ds_read_b128 v[180:183], v114 offset:1024
	ds_read_b128 v[184:187], v114 offset:2048
	ds_read_b128 v[188:191], v114 offset:3072
	s_add_u32 s86, s86, 0x100000
	s_addc_u32 s87, s87, 0
	s_mov_b32 m0, s9
	v_lshl_add_u64 v[246:247], s[86:87], 0, v[146:147]
	ds_read_b128 v[192:195], v141 offset:32768
	ds_read_b128 v[196:199], v141 offset:33792
	ds_read_b128 v[210:213], v141 offset:34816
	ds_read_b128 v[214:217], v141 offset:35840
	ds_read_b128 v[218:221], v141 offset:36864
	ds_read_b128 v[222:225], v141 offset:37888
	ds_read_b128 v[226:229], v141 offset:38912
	ds_read_b128 v[236:239], v141 offset:39936
	global_load_lds_dwordx4 v[246:247], off
	v_lshl_add_u64 v[246:247], s[86:87], 0, v[150:151]
	s_mov_b32 m0, s10
	s_nop 0
	global_load_lds_dwordx4 v[246:247], off
	s_waitcnt vmcnt(8)
	s_waitcnt lgkmcnt(0)
	s_setprio 1
	s_barrier
	v_mfma_f32_16x16x32_bf16 v[132:135], v[160:163], v[192:195], v[132:135]
	v_mfma_f32_16x16x32_bf16 v[128:131], v[168:171], v[192:195], v[128:131]
	v_mfma_f32_16x16x32_bf16 v[124:127], v[160:163], v[210:213], v[124:127]
	v_mfma_f32_16x16x32_bf16 v[110:113], v[168:171], v[210:213], v[110:113]
	v_mfma_f32_16x16x32_bf16 v[102:105], v[160:163], v[218:221], v[102:105]
	v_mfma_f32_16x16x32_bf16 v[94:97], v[168:171], v[218:221], v[94:97]
	v_mfma_f32_16x16x32_bf16 v[86:89], v[160:163], v[226:229], v[86:89]
	v_mfma_f32_16x16x32_bf16 v[78:81], v[168:171], v[226:229], v[78:81]
	v_mfma_f32_16x16x32_bf16 v[132:135], v[164:167], v[196:199], v[132:135]
	v_mfma_f32_16x16x32_bf16 v[128:131], v[172:175], v[196:199], v[128:131]
	v_mfma_f32_16x16x32_bf16 v[124:127], v[164:167], v[214:217], v[124:127]
	v_mfma_f32_16x16x32_bf16 v[110:113], v[172:175], v[214:217], v[110:113]
	v_mfma_f32_16x16x32_bf16 v[102:105], v[164:167], v[222:225], v[102:105]
	v_mfma_f32_16x16x32_bf16 v[94:97], v[172:175], v[222:225], v[94:97]
	v_mfma_f32_16x16x32_bf16 v[86:89], v[164:167], v[236:239], v[86:89]
	v_mfma_f32_16x16x32_bf16 v[78:81], v[172:175], v[236:239], v[78:81]
	v_mfma_f32_16x16x32_bf16 v[120:123], v[176:179], v[192:195], v[120:123]
	v_mfma_f32_16x16x32_bf16 v[106:109], v[184:187], v[192:195], v[106:109]
	v_mfma_f32_16x16x32_bf16 v[98:101], v[176:179], v[210:213], v[98:101]
	v_mfma_f32_16x16x32_bf16 v[90:93], v[184:187], v[210:213], v[90:93]
	v_mfma_f32_16x16x32_bf16 v[82:85], v[176:179], v[218:221], v[82:85]
	v_mfma_f32_16x16x32_bf16 v[74:77], v[184:187], v[218:221], v[74:77]
	v_mfma_f32_16x16x32_bf16 v[70:73], v[176:179], v[226:229], v[70:73]
	v_mfma_f32_16x16x32_bf16 v[66:69], v[184:187], v[226:229], v[66:69]
	v_mfma_f32_16x16x32_bf16 v[120:123], v[180:183], v[196:199], v[120:123]
	v_mfma_f32_16x16x32_bf16 v[106:109], v[188:191], v[196:199], v[106:109]
	v_mfma_f32_16x16x32_bf16 v[98:101], v[180:183], v[214:217], v[98:101]
	v_mfma_f32_16x16x32_bf16 v[90:93], v[188:191], v[214:217], v[90:93]
	v_mfma_f32_16x16x32_bf16 v[82:85], v[180:183], v[222:225], v[82:85]
	v_mfma_f32_16x16x32_bf16 v[74:77], v[188:191], v[222:225], v[74:77]
	v_mfma_f32_16x16x32_bf16 v[70:73], v[180:183], v[236:239], v[70:73]
	v_mfma_f32_16x16x32_bf16 v[66:69], v[188:191], v[236:239], v[66:69]
	s_barrier
	s_setprio 0
	s_add_i32 s33, s33, s6
	v_lshl_add_u64 v[202:203], v[202:203], 0, s[20:21]
	s_mov_b32 m0, s33
	ds_read_b128 v[192:195], v141 offset:49152
	ds_read_b128 v[196:199], v141 offset:50176
	ds_read_b128 v[210:213], v141 offset:51200
	ds_read_b128 v[214:217], v141 offset:52224
	ds_read_b128 v[218:221], v141 offset:53248
	ds_read_b128 v[222:225], v141 offset:54272
	ds_read_b128 v[226:229], v141 offset:55296
	ds_read_b128 v[236:239], v141 offset:56320
	global_load_lds_dwordx4 v[202:203], off
	s_add_i32 m0, s33, 0x2000
	s_add_u32 s84, s84, 0x100080
	v_lshl_add_u64 v[202:203], v[240:241], 0, s[20:21]
	s_addc_u32 s85, s85, 0
	s_add_i32 s33, s73, s6
	global_load_lds_dwordx4 v[202:203], off
	v_lshl_add_u64 v[202:203], s[84:85], 0, v[148:149]
	s_mov_b32 m0, s33
	s_nop 0
	global_load_lds_dwordx4 v[202:203], off
	v_lshl_add_u64 v[202:203], s[84:85], 0, v[152:153]
	s_add_i32 m0, s33, 0x2000
	s_nop 0
	global_load_lds_dwordx4 v[202:203], off
	v_lshl_add_u64 v[202:203], v[242:243], 0, s[20:21]
	s_mov_b32 m0, s11
	s_nop 0
	global_load_lds_dwordx4 v[202:203], off
	v_lshl_add_u64 v[202:203], v[244:245], 0, s[20:21]
	s_mov_b32 m0, s12
	s_nop 0
	global_load_lds_dwordx4 v[202:203], off
	s_waitcnt vmcnt(8)
	s_waitcnt lgkmcnt(0)
	s_setprio 1
	s_barrier
	v_mfma_f32_16x16x32_bf16 v[62:65], v[160:163], v[192:195], v[62:65]
	v_mfma_f32_16x16x32_bf16 v[58:61], v[168:171], v[192:195], v[58:61]
	v_mfma_f32_16x16x32_bf16 v[54:57], v[160:163], v[210:213], v[54:57]
	v_mfma_f32_16x16x32_bf16 v[46:49], v[168:171], v[210:213], v[46:49]
	v_mfma_f32_16x16x32_bf16 v[38:41], v[160:163], v[218:221], v[38:41]
	v_mfma_f32_16x16x32_bf16 v[30:33], v[168:171], v[218:221], v[30:33]
	v_mfma_f32_16x16x32_bf16 v[22:25], v[160:163], v[226:229], v[22:25]
	v_mfma_f32_16x16x32_bf16 v[14:17], v[168:171], v[226:229], v[14:17]
	v_mfma_f32_16x16x32_bf16 v[62:65], v[164:167], v[196:199], v[62:65]
	v_mfma_f32_16x16x32_bf16 v[58:61], v[172:175], v[196:199], v[58:61]
	v_mfma_f32_16x16x32_bf16 v[54:57], v[164:167], v[214:217], v[54:57]
	v_mfma_f32_16x16x32_bf16 v[46:49], v[172:175], v[214:217], v[46:49]
	v_mfma_f32_16x16x32_bf16 v[38:41], v[164:167], v[222:225], v[38:41]
	v_mfma_f32_16x16x32_bf16 v[30:33], v[172:175], v[222:225], v[30:33]
	v_mfma_f32_16x16x32_bf16 v[22:25], v[164:167], v[236:239], v[22:25]
	v_mfma_f32_16x16x32_bf16 v[14:17], v[172:175], v[236:239], v[14:17]
	v_mfma_f32_16x16x32_bf16 v[50:53], v[176:179], v[192:195], v[50:53]
	v_mfma_f32_16x16x32_bf16 v[42:45], v[184:187], v[192:195], v[42:45]
	v_mfma_f32_16x16x32_bf16 v[34:37], v[176:179], v[210:213], v[34:37]
	v_mfma_f32_16x16x32_bf16 v[26:29], v[184:187], v[210:213], v[26:29]
	v_mfma_f32_16x16x32_bf16 v[18:21], v[176:179], v[218:221], v[18:21]
	v_mfma_f32_16x16x32_bf16 v[10:13], v[184:187], v[218:221], v[10:13]
	v_mfma_f32_16x16x32_bf16 v[6:9], v[176:179], v[226:229], v[6:9]
	v_mfma_f32_16x16x32_bf16 v[2:5], v[184:187], v[226:229], v[2:5]
	v_mfma_f32_16x16x32_bf16 v[50:53], v[180:183], v[196:199], v[50:53]
	v_mfma_f32_16x16x32_bf16 v[42:45], v[188:191], v[196:199], v[42:45]
	v_mfma_f32_16x16x32_bf16 v[34:37], v[180:183], v[214:217], v[34:37]
	v_mfma_f32_16x16x32_bf16 v[26:29], v[188:191], v[214:217], v[26:29]
	v_mfma_f32_16x16x32_bf16 v[18:21], v[180:183], v[222:225], v[18:21]
	v_mfma_f32_16x16x32_bf16 v[10:13], v[188:191], v[222:225], v[10:13]
	v_mfma_f32_16x16x32_bf16 v[6:9], v[180:183], v[236:239], v[6:9]
	v_mfma_f32_16x16x32_bf16 v[2:5], v[188:191], v[236:239], v[2:5]
	s_barrier
	s_setprio 0
	s_add_i32 s19, s19, 2
	s_add_u32 s38, s38, 0x100
	s_addc_u32 s39, s39, 0
	s_add_u32 s17, s17, 0x100
	s_addc_u32 s18, s18, 0
	s_cmp_gt_u32 s19, 61
	s_cbranch_scc0 .LBB0_230
	s_and_b64 vcc, exec, s[30:31]
	s_cbranch_vccz .LBB0_233
	s_barrier

.LBB0_460:
	s_add_u32 s10, s24, 0xfffc0080
	s_addc_u32 s11, s25, -1
	s_add_i32 s12, 0, 0x10000
	s_cmp_eq_u32 s9, 12
	s_cselect_b32 s31, s1, s11
	s_cselect_b32 s30, s4, s10
	v_add_u32_e32 v114, s12, v119
	s_cselect_b32 s27, s5, s8
	s_cselect_b32 s26, s6, s7
	s_add_i32 s13, 0, 0x14000
	ds_read_b128 v[136:139], v114
	ds_read_b128 v[140:143], v114 offset:1024
	ds_read_b128 v[144:147], v114 offset:2048
	ds_read_b128 v[148:151], v114 offset:3072
	v_add_u32_e32 v114, s13, v119
	ds_read_b128 v[182:185], v114
	ds_read_b128 v[186:189], v114 offset:1024
	ds_read_b128 v[190:193], v114 offset:2048
	ds_read_b128 v[194:197], v114 offset:3072
	v_lshl_add_u64 v[170:171], s[24:25], 0, v[166:167]
	s_add_i32 m0, s53, 0xc000
	ds_read_b128 v[210:213], v181
	ds_read_b128 v[214:217], v181 offset:1024
	ds_read_b128 v[218:221], v181 offset:2048
	ds_read_b128 v[222:225], v181 offset:3072
	ds_read_b128 v[226:229], v181 offset:4096
	ds_read_b128 v[236:239], v181 offset:5120
	ds_read_b128 v[240:243], v181 offset:6144
	ds_read_b128 v[244:247], v181 offset:7168
	global_load_lds_dwordx4 v[170:171], off
	v_lshl_add_u64 v[170:171], s[24:25], 0, v[168:169]
	s_add_i32 m0, s53, 0xe000
	s_nop 0
	global_load_lds_dwordx4 v[170:171], off
	s_waitcnt vmcnt(8)
	s_waitcnt lgkmcnt(0)
	s_setprio 1
	s_barrier
	v_mfma_f32_16x16x32_bf16 v[132:135], v[136:139], v[210:213], v[132:135]
	v_mfma_f32_16x16x32_bf16 v[128:131], v[144:147], v[210:213], v[128:131]
	v_mfma_f32_16x16x32_bf16 v[120:123], v[136:139], v[218:221], v[120:123]
	v_mfma_f32_16x16x32_bf16 v[106:109], v[144:147], v[218:221], v[106:109]
	v_mfma_f32_16x16x32_bf16 v[98:101], v[136:139], v[226:229], v[98:101]
	v_mfma_f32_16x16x32_bf16 v[90:93], v[144:147], v[226:229], v[90:93]
	v_mfma_f32_16x16x32_bf16 v[82:85], v[136:139], v[240:243], v[82:85]
	v_mfma_f32_16x16x32_bf16 v[74:77], v[144:147], v[240:243], v[74:77]
	v_mfma_f32_16x16x32_bf16 v[132:135], v[140:143], v[214:217], v[132:135]
	v_mfma_f32_16x16x32_bf16 v[128:131], v[148:151], v[214:217], v[128:131]
	v_mfma_f32_16x16x32_bf16 v[120:123], v[140:143], v[222:225], v[120:123]
	v_mfma_f32_16x16x32_bf16 v[106:109], v[148:151], v[222:225], v[106:109]
	v_mfma_f32_16x16x32_bf16 v[98:101], v[140:143], v[236:239], v[98:101]
	v_mfma_f32_16x16x32_bf16 v[90:93], v[148:151], v[236:239], v[90:93]
	v_mfma_f32_16x16x32_bf16 v[82:85], v[140:143], v[244:247], v[82:85]
	v_mfma_f32_16x16x32_bf16 v[74:77], v[148:151], v[244:247], v[74:77]
	v_mfma_f32_16x16x32_bf16 v[124:127], v[182:185], v[210:213], v[124:127]
	v_mfma_f32_16x16x32_bf16 v[110:113], v[190:193], v[210:213], v[110:113]
	v_mfma_f32_16x16x32_bf16 v[102:105], v[182:185], v[218:221], v[102:105]
	v_mfma_f32_16x16x32_bf16 v[94:97], v[190:193], v[218:221], v[94:97]
	v_mfma_f32_16x16x32_bf16 v[86:89], v[182:185], v[226:229], v[86:89]
	v_mfma_f32_16x16x32_bf16 v[78:81], v[190:193], v[226:229], v[78:81]
	v_mfma_f32_16x16x32_bf16 v[70:73], v[182:185], v[240:243], v[70:73]
	v_mfma_f32_16x16x32_bf16 v[66:69], v[190:193], v[240:243], v[66:69]
	v_mfma_f32_16x16x32_bf16 v[124:127], v[186:189], v[214:217], v[124:127]
	v_mfma_f32_16x16x32_bf16 v[110:113], v[194:197], v[214:217], v[110:113]
	v_mfma_f32_16x16x32_bf16 v[102:105], v[186:189], v[222:225], v[102:105]
	v_mfma_f32_16x16x32_bf16 v[94:97], v[194:197], v[222:225], v[94:97]
	v_mfma_f32_16x16x32_bf16 v[86:89], v[186:189], v[236:239], v[86:89]
	v_mfma_f32_16x16x32_bf16 v[78:81], v[194:197], v[236:239], v[78:81]
	v_mfma_f32_16x16x32_bf16 v[70:73], v[186:189], v[244:247], v[70:73]
	v_mfma_f32_16x16x32_bf16 v[66:69], v[194:197], v[244:247], v[66:69]
	s_barrier
	s_setprio 0
	s_add_i32 s10, s12, s58
	v_lshl_add_u64 v[170:171], s[26:27], 0, v[152:153]
	s_mov_b32 m0, s10
	ds_read_b128 v[210:213], v181 offset:16384
	ds_read_b128 v[214:217], v181 offset:17408
	ds_read_b128 v[218:221], v181 offset:18432
	ds_read_b128 v[222:225], v181 offset:19456
	ds_read_b128 v[226:229], v181 offset:20480
	ds_read_b128 v[236:239], v181 offset:21504
	ds_read_b128 v[240:243], v181 offset:22528
	ds_read_b128 v[244:247], v181 offset:23552
	global_load_lds_dwordx4 v[170:171], off
	s_add_i32 m0, s10, 0x2000
	s_add_u32 s10, s26, 0x40000
	v_lshl_add_u64 v[198:199], s[26:27], 0, v[156:157]
	s_addc_u32 s11, s27, 0
	s_add_i32 s12, s13, s58
	global_load_lds_dwordx4 v[198:199], off
	v_lshl_add_u64 v[202:203], s[10:11], 0, v[152:153]
	s_mov_b32 m0, s12
	v_lshl_add_u64 v[248:249], s[30:31], 0, v[154:155]
	global_load_lds_dwordx4 v[202:203], off
	v_lshl_add_u64 v[202:203], s[10:11], 0, v[156:157]
	s_add_i32 m0, s12, 0x2000
	s_nop 0
	global_load_lds_dwordx4 v[202:203], off
	v_lshl_add_u64 v[202:203], s[30:31], 0, v[116:117]
	s_mov_b32 m0, s53
	s_nop 0
	global_load_lds_dwordx4 v[202:203], off
	s_mov_b32 m0, s59
	s_nop 0
	global_load_lds_dwordx4 v[248:249], off
	s_waitcnt vmcnt(8)
	s_waitcnt lgkmcnt(0)
	s_setprio 1
	s_barrier
	v_mfma_f32_16x16x32_bf16 v[62:65], v[136:139], v[210:213], v[62:65]
	v_mfma_f32_16x16x32_bf16 v[58:61], v[144:147], v[210:213], v[58:61]
	v_mfma_f32_16x16x32_bf16 v[50:53], v[136:139], v[218:221], v[50:53]
	v_mfma_f32_16x16x32_bf16 v[42:45], v[144:147], v[218:221], v[42:45]
	v_mfma_f32_16x16x32_bf16 v[34:37], v[136:139], v[226:229], v[34:37]
	v_mfma_f32_16x16x32_bf16 v[26:29], v[144:147], v[226:229], v[26:29]
	v_mfma_f32_16x16x32_bf16 v[14:17], v[136:139], v[240:243], v[14:17]
	v_mfma_f32_16x16x32_bf16 v[10:13], v[144:147], v[240:243], v[10:13]
	v_mfma_f32_16x16x32_bf16 v[62:65], v[140:143], v[214:217], v[62:65]
	v_mfma_f32_16x16x32_bf16 v[58:61], v[148:151], v[214:217], v[58:61]
	v_mfma_f32_16x16x32_bf16 v[50:53], v[140:143], v[222:225], v[50:53]
	v_mfma_f32_16x16x32_bf16 v[42:45], v[148:151], v[222:225], v[42:45]
	v_mfma_f32_16x16x32_bf16 v[34:37], v[140:143], v[236:239], v[34:37]
	v_mfma_f32_16x16x32_bf16 v[26:29], v[148:151], v[236:239], v[26:29]
	v_mfma_f32_16x16x32_bf16 v[14:17], v[140:143], v[244:247], v[14:17]
	v_mfma_f32_16x16x32_bf16 v[10:13], v[148:151], v[244:247], v[10:13]
	v_mfma_f32_16x16x32_bf16 v[54:57], v[182:185], v[210:213], v[54:57]
	v_mfma_f32_16x16x32_bf16 v[46:49], v[190:193], v[210:213], v[46:49]
	v_mfma_f32_16x16x32_bf16 v[38:41], v[182:185], v[218:221], v[38:41]
	v_mfma_f32_16x16x32_bf16 v[30:33], v[190:193], v[218:221], v[30:33]
	v_mfma_f32_16x16x32_bf16 v[22:25], v[182:185], v[226:229], v[22:25]
	v_mfma_f32_16x16x32_bf16 v[18:21], v[190:193], v[226:229], v[18:21]
	v_mfma_f32_16x16x32_bf16 v[6:9], v[182:185], v[240:243], v[6:9]
	v_mfma_f32_16x16x32_bf16 v[2:5], v[190:193], v[240:243], v[2:5]
	v_mfma_f32_16x16x32_bf16 v[54:57], v[186:189], v[214:217], v[54:57]
	v_mfma_f32_16x16x32_bf16 v[46:49], v[194:197], v[214:217], v[46:49]
	v_mfma_f32_16x16x32_bf16 v[38:41], v[186:189], v[222:225], v[38:41]
	v_mfma_f32_16x16x32_bf16 v[30:33], v[194:197], v[222:225], v[30:33]
	v_mfma_f32_16x16x32_bf16 v[22:25], v[186:189], v[236:239], v[22:25]
	v_mfma_f32_16x16x32_bf16 v[18:21], v[194:197], v[236:239], v[18:21]
	v_mfma_f32_16x16x32_bf16 v[6:9], v[186:189], v[244:247], v[6:9]
	v_mfma_f32_16x16x32_bf16 v[2:5], v[194:197], v[244:247], v[2:5]
	s_barrier
	s_setprio 0
	s_add_i32 s12, 0, 0x18000
	v_add_u32_e32 v114, s12, v119
	s_add_i32 s13, 0, 0x1c000
	ds_read_b128 v[136:139], v114
	ds_read_b128 v[140:143], v114 offset:1024
	ds_read_b128 v[144:147], v114 offset:2048
	ds_read_b128 v[148:151], v114 offset:3072
	v_add_u32_e32 v114, s13, v119
	ds_read_b128 v[182:185], v114
	ds_read_b128 v[186:189], v114 offset:1024
	ds_read_b128 v[190:193], v114 offset:2048
	ds_read_b128 v[194:197], v114 offset:3072
	s_add_u32 s10, s30, 0x40000
	s_addc_u32 s11, s31, 0
	s_mov_b32 m0, s60
	v_lshl_add_u64 v[250:251], s[10:11], 0, v[116:117]
	ds_read_b128 v[210:213], v181 offset:32768
	ds_read_b128 v[214:217], v181 offset:33792
	ds_read_b128 v[218:221], v181 offset:34816
	ds_read_b128 v[222:225], v181 offset:35840
	ds_read_b128 v[226:229], v181 offset:36864
	ds_read_b128 v[236:239], v181 offset:37888
	ds_read_b128 v[240:243], v181 offset:38912
	ds_read_b128 v[244:247], v181 offset:39936
	global_load_lds_dwordx4 v[250:251], off
	v_lshl_add_u64 v[250:251], s[10:11], 0, v[154:155]
	s_mov_b32 m0, s61
	s_nop 0
	global_load_lds_dwordx4 v[250:251], off
	s_waitcnt vmcnt(8)
	s_waitcnt lgkmcnt(0)
	s_setprio 1
	s_barrier
	v_mfma_f32_16x16x32_bf16 v[132:135], v[136:139], v[210:213], v[132:135]
	v_mfma_f32_16x16x32_bf16 v[128:131], v[144:147], v[210:213], v[128:131]
	v_mfma_f32_16x16x32_bf16 v[120:123], v[136:139], v[218:221], v[120:123]
	v_mfma_f32_16x16x32_bf16 v[106:109], v[144:147], v[218:221], v[106:109]
	v_mfma_f32_16x16x32_bf16 v[98:101], v[136:139], v[226:229], v[98:101]
	v_mfma_f32_16x16x32_bf16 v[90:93], v[144:147], v[226:229], v[90:93]
	v_mfma_f32_16x16x32_bf16 v[82:85], v[136:139], v[240:243], v[82:85]
	v_mfma_f32_16x16x32_bf16 v[74:77], v[144:147], v[240:243], v[74:77]
	v_mfma_f32_16x16x32_bf16 v[132:135], v[140:143], v[214:217], v[132:135]
	v_mfma_f32_16x16x32_bf16 v[128:131], v[148:151], v[214:217], v[128:131]
	v_mfma_f32_16x16x32_bf16 v[120:123], v[140:143], v[222:225], v[120:123]
	v_mfma_f32_16x16x32_bf16 v[106:109], v[148:151], v[222:225], v[106:109]
	v_mfma_f32_16x16x32_bf16 v[98:101], v[140:143], v[236:239], v[98:101]
	v_mfma_f32_16x16x32_bf16 v[90:93], v[148:151], v[236:239], v[90:93]
	v_mfma_f32_16x16x32_bf16 v[82:85], v[140:143], v[244:247], v[82:85]
	v_mfma_f32_16x16x32_bf16 v[74:77], v[148:151], v[244:247], v[74:77]
	v_mfma_f32_16x16x32_bf16 v[124:127], v[182:185], v[210:213], v[124:127]
	v_mfma_f32_16x16x32_bf16 v[110:113], v[190:193], v[210:213], v[110:113]
	v_mfma_f32_16x16x32_bf16 v[102:105], v[182:185], v[218:221], v[102:105]
	v_mfma_f32_16x16x32_bf16 v[94:97], v[190:193], v[218:221], v[94:97]
	v_mfma_f32_16x16x32_bf16 v[86:89], v[182:185], v[226:229], v[86:89]
	v_mfma_f32_16x16x32_bf16 v[78:81], v[190:193], v[226:229], v[78:81]
	v_mfma_f32_16x16x32_bf16 v[70:73], v[182:185], v[240:243], v[70:73]
	v_mfma_f32_16x16x32_bf16 v[66:69], v[190:193], v[240:243], v[66:69]
	v_mfma_f32_16x16x32_bf16 v[124:127], v[186:189], v[214:217], v[124:127]
	v_mfma_f32_16x16x32_bf16 v[110:113], v[194:197], v[214:217], v[110:113]
	v_mfma_f32_16x16x32_bf16 v[102:105], v[186:189], v[222:225], v[102:105]
	v_mfma_f32_16x16x32_bf16 v[94:97], v[194:197], v[222:225], v[94:97]
	v_mfma_f32_16x16x32_bf16 v[86:89], v[186:189], v[236:239], v[86:89]
	v_mfma_f32_16x16x32_bf16 v[78:81], v[194:197], v[236:239], v[78:81]
	v_mfma_f32_16x16x32_bf16 v[70:73], v[186:189], v[244:247], v[70:73]
	v_mfma_f32_16x16x32_bf16 v[66:69], v[194:197], v[244:247], v[66:69]
	s_barrier
	s_setprio 0
	s_add_i32 s10, s12, s58
	v_lshl_add_u64 v[170:171], v[170:171], 0, s[20:21]
	s_mov_b32 m0, s10
	ds_read_b128 v[210:213], v181 offset:49152
	ds_read_b128 v[214:217], v181 offset:50176
	ds_read_b128 v[218:221], v181 offset:51200
	ds_read_b128 v[222:225], v181 offset:52224
	ds_read_b128 v[226:229], v181 offset:53248
	ds_read_b128 v[236:239], v181 offset:54272
	ds_read_b128 v[240:243], v181 offset:55296
	ds_read_b128 v[244:247], v181 offset:56320
	global_load_lds_dwordx4 v[170:171], off
	s_add_i32 m0, s10, 0x2000
	s_add_u32 s10, s26, 0x40080
	v_lshl_add_u64 v[170:171], v[198:199], 0, s[20:21]
	s_addc_u32 s11, s27, 0
	s_add_i32 s12, s13, s58
	global_load_lds_dwordx4 v[170:171], off
	v_lshl_add_u64 v[170:171], s[10:11], 0, v[152:153]
	s_mov_b32 m0, s12
	s_nop 0
	global_load_lds_dwordx4 v[170:171], off
	v_lshl_add_u64 v[170:171], s[10:11], 0, v[156:157]
	s_add_i32 m0, s12, 0x2000
	s_nop 0
	global_load_lds_dwordx4 v[170:171], off
	v_lshl_add_u64 v[170:171], v[202:203], 0, s[20:21]
	s_mov_b32 m0, s62
	s_nop 0
	global_load_lds_dwordx4 v[170:171], off
	v_lshl_add_u64 v[170:171], v[248:249], 0, s[20:21]
	s_mov_b32 m0, s63
	s_nop 0
	global_load_lds_dwordx4 v[170:171], off
	s_waitcnt vmcnt(8)
	s_waitcnt lgkmcnt(0)
	s_setprio 1
	s_barrier
	v_mfma_f32_16x16x32_bf16 v[62:65], v[136:139], v[210:213], v[62:65]
	v_mfma_f32_16x16x32_bf16 v[58:61], v[144:147], v[210:213], v[58:61]
	v_mfma_f32_16x16x32_bf16 v[50:53], v[136:139], v[218:221], v[50:53]
	v_mfma_f32_16x16x32_bf16 v[42:45], v[144:147], v[218:221], v[42:45]
	v_mfma_f32_16x16x32_bf16 v[34:37], v[136:139], v[226:229], v[34:37]
	v_mfma_f32_16x16x32_bf16 v[26:29], v[144:147], v[226:229], v[26:29]
	v_mfma_f32_16x16x32_bf16 v[14:17], v[136:139], v[240:243], v[14:17]
	v_mfma_f32_16x16x32_bf16 v[10:13], v[144:147], v[240:243], v[10:13]
	v_mfma_f32_16x16x32_bf16 v[62:65], v[140:143], v[214:217], v[62:65]
	v_mfma_f32_16x16x32_bf16 v[58:61], v[148:151], v[214:217], v[58:61]
	v_mfma_f32_16x16x32_bf16 v[50:53], v[140:143], v[222:225], v[50:53]
	v_mfma_f32_16x16x32_bf16 v[42:45], v[148:151], v[222:225], v[42:45]
	v_mfma_f32_16x16x32_bf16 v[34:37], v[140:143], v[236:239], v[34:37]
	v_mfma_f32_16x16x32_bf16 v[26:29], v[148:151], v[236:239], v[26:29]
	v_mfma_f32_16x16x32_bf16 v[14:17], v[140:143], v[244:247], v[14:17]
	v_mfma_f32_16x16x32_bf16 v[10:13], v[148:151], v[244:247], v[10:13]
	v_mfma_f32_16x16x32_bf16 v[54:57], v[182:185], v[210:213], v[54:57]
	v_mfma_f32_16x16x32_bf16 v[46:49], v[190:193], v[210:213], v[46:49]
	v_mfma_f32_16x16x32_bf16 v[38:41], v[182:185], v[218:221], v[38:41]
	v_mfma_f32_16x16x32_bf16 v[30:33], v[190:193], v[218:221], v[30:33]
	v_mfma_f32_16x16x32_bf16 v[22:25], v[182:185], v[226:229], v[22:25]
	v_mfma_f32_16x16x32_bf16 v[18:21], v[190:193], v[226:229], v[18:21]
	v_mfma_f32_16x16x32_bf16 v[6:9], v[182:185], v[240:243], v[6:9]
	v_mfma_f32_16x16x32_bf16 v[2:5], v[190:193], v[240:243], v[2:5]
	v_mfma_f32_16x16x32_bf16 v[54:57], v[186:189], v[214:217], v[54:57]
	v_mfma_f32_16x16x32_bf16 v[46:49], v[194:197], v[214:217], v[46:49]
	v_mfma_f32_16x16x32_bf16 v[38:41], v[186:189], v[222:225], v[38:41]
	v_mfma_f32_16x16x32_bf16 v[30:33], v[194:197], v[222:225], v[30:33]
	v_mfma_f32_16x16x32_bf16 v[22:25], v[186:189], v[236:239], v[22:25]
	v_mfma_f32_16x16x32_bf16 v[18:21], v[194:197], v[236:239], v[18:21]
	v_mfma_f32_16x16x32_bf16 v[6:9], v[186:189], v[244:247], v[6:9]
	v_mfma_f32_16x16x32_bf16 v[2:5], v[194:197], v[244:247], v[2:5]
	s_barrier
	s_setprio 0
	s_add_i32 s9, s9, 2
	s_add_u32 s24, s24, 0x100
	s_addc_u32 s25, s25, 0
	s_add_u32 s7, s7, 0x100
	s_addc_u32 s8, s8, 0
	s_cmp_gt_u32 s9, 13
	s_cbranch_scc0 .LBB0_460
	s_and_b64 vcc, exec, s[22:23]
	s_cbranch_vccz .LBB0_463
	s_barrier

.LBB0_514:
	s_add_u32 s10, s48, 0xfffe0080
	s_addc_u32 s11, s49, -1
	s_add_i32 s12, 0, 0x10000
	s_cmp_eq_u32 s9, 4
	s_cselect_b32 s53, s1, s11
	s_cselect_b32 s52, s4, s10
	v_add_u32_e32 v114, s12, v119
	s_cselect_b32 s51, s5, s8
	s_cselect_b32 s50, s6, s7
	s_add_i32 s13, 0, 0x14000
	ds_read_b128 v[136:139], v114
	ds_read_b128 v[140:143], v114 offset:1024
	ds_read_b128 v[158:161], v114 offset:2048
	ds_read_b128 v[162:165], v114 offset:3072
	v_add_u32_e32 v114, s13, v119
	ds_read_b128 v[170:173], v114
	ds_read_b128 v[174:177], v114 offset:1024
	ds_read_b128 v[178:181], v114 offset:2048
	ds_read_b128 v[182:185], v114 offset:3072
	v_lshl_add_u64 v[166:167], s[48:49], 0, v[154:155]
	s_add_i32 m0, s31, 0xc000
	ds_read_b128 v[186:189], v169
	ds_read_b128 v[190:193], v169 offset:1024
	ds_read_b128 v[194:197], v169 offset:2048
	ds_read_b128 v[210:213], v169 offset:3072
	ds_read_b128 v[214:217], v169 offset:4096
	ds_read_b128 v[218:221], v169 offset:5120
	ds_read_b128 v[222:225], v169 offset:6144
	ds_read_b128 v[226:229], v169 offset:7168
	global_load_lds_dwordx4 v[166:167], off
	v_lshl_add_u64 v[166:167], s[48:49], 0, v[156:157]
	s_add_i32 m0, s31, 0xe000
	s_nop 0
	global_load_lds_dwordx4 v[166:167], off
	s_waitcnt vmcnt(8)
	s_waitcnt lgkmcnt(0)
	s_setprio 1
	s_barrier
	v_mfma_f32_16x16x32_bf16 v[132:135], v[136:139], v[186:189], v[132:135]
	v_mfma_f32_16x16x32_bf16 v[128:131], v[158:161], v[186:189], v[128:131]
	v_mfma_f32_16x16x32_bf16 v[110:113], v[136:139], v[194:197], v[110:113]
	v_mfma_f32_16x16x32_bf16 v[106:109], v[158:161], v[194:197], v[106:109]
	v_mfma_f32_16x16x32_bf16 v[94:97], v[136:139], v[214:217], v[94:97]
	v_mfma_f32_16x16x32_bf16 v[90:93], v[158:161], v[214:217], v[90:93]
	v_mfma_f32_16x16x32_bf16 v[78:81], v[136:139], v[222:225], v[78:81]
	v_mfma_f32_16x16x32_bf16 v[74:77], v[158:161], v[222:225], v[74:77]
	v_mfma_f32_16x16x32_bf16 v[132:135], v[140:143], v[190:193], v[132:135]
	v_mfma_f32_16x16x32_bf16 v[128:131], v[162:165], v[190:193], v[128:131]
	v_mfma_f32_16x16x32_bf16 v[110:113], v[140:143], v[210:213], v[110:113]
	v_mfma_f32_16x16x32_bf16 v[106:109], v[162:165], v[210:213], v[106:109]
	v_mfma_f32_16x16x32_bf16 v[94:97], v[140:143], v[218:221], v[94:97]
	v_mfma_f32_16x16x32_bf16 v[90:93], v[162:165], v[218:221], v[90:93]
	v_mfma_f32_16x16x32_bf16 v[78:81], v[140:143], v[226:229], v[78:81]
	v_mfma_f32_16x16x32_bf16 v[74:77], v[162:165], v[226:229], v[74:77]
	v_mfma_f32_16x16x32_bf16 v[124:127], v[170:173], v[186:189], v[124:127]
	v_mfma_f32_16x16x32_bf16 v[120:123], v[178:181], v[186:189], v[120:123]
	v_mfma_f32_16x16x32_bf16 v[102:105], v[170:173], v[194:197], v[102:105]
	v_mfma_f32_16x16x32_bf16 v[98:101], v[178:181], v[194:197], v[98:101]
	v_mfma_f32_16x16x32_bf16 v[86:89], v[170:173], v[214:217], v[86:89]
	v_mfma_f32_16x16x32_bf16 v[82:85], v[178:181], v[214:217], v[82:85]
	v_mfma_f32_16x16x32_bf16 v[70:73], v[170:173], v[222:225], v[70:73]
	v_mfma_f32_16x16x32_bf16 v[66:69], v[178:181], v[222:225], v[66:69]
	v_mfma_f32_16x16x32_bf16 v[124:127], v[174:177], v[190:193], v[124:127]
	v_mfma_f32_16x16x32_bf16 v[120:123], v[182:185], v[190:193], v[120:123]
	v_mfma_f32_16x16x32_bf16 v[102:105], v[174:177], v[210:213], v[102:105]
	v_mfma_f32_16x16x32_bf16 v[98:101], v[182:185], v[210:213], v[98:101]
	v_mfma_f32_16x16x32_bf16 v[86:89], v[174:177], v[218:221], v[86:89]
	v_mfma_f32_16x16x32_bf16 v[82:85], v[182:185], v[218:221], v[82:85]
	v_mfma_f32_16x16x32_bf16 v[70:73], v[174:177], v[226:229], v[70:73]
	v_mfma_f32_16x16x32_bf16 v[66:69], v[182:185], v[226:229], v[66:69]
	s_barrier
	s_setprio 0
	s_add_i32 s10, s12, s60
	v_lshl_add_u64 v[166:167], s[50:51], 0, v[144:145]
	s_mov_b32 m0, s10
	ds_read_b128 v[186:189], v169 offset:16384
	ds_read_b128 v[190:193], v169 offset:17408
	ds_read_b128 v[194:197], v169 offset:18432
	ds_read_b128 v[210:213], v169 offset:19456
	ds_read_b128 v[214:217], v169 offset:20480
	ds_read_b128 v[218:221], v169 offset:21504
	ds_read_b128 v[222:225], v169 offset:22528
	ds_read_b128 v[226:229], v169 offset:23552
	global_load_lds_dwordx4 v[166:167], off
	s_add_i32 m0, s10, 0x2000
	s_add_u32 s10, s50, 0x20000
	v_lshl_add_u64 v[198:199], s[50:51], 0, v[148:149]
	s_addc_u32 s11, s51, 0
	s_add_i32 s12, s13, s60
	global_load_lds_dwordx4 v[198:199], off
	v_lshl_add_u64 v[202:203], s[10:11], 0, v[144:145]
	s_mov_b32 m0, s12
	v_lshl_add_u64 v[236:237], s[52:53], 0, v[146:147]
	global_load_lds_dwordx4 v[202:203], off
	v_lshl_add_u64 v[202:203], s[10:11], 0, v[148:149]
	s_add_i32 m0, s12, 0x2000
	s_nop 0
	global_load_lds_dwordx4 v[202:203], off
	v_lshl_add_u64 v[202:203], s[52:53], 0, v[116:117]
	s_mov_b32 m0, s31
	s_nop 0
	global_load_lds_dwordx4 v[202:203], off
	s_mov_b32 m0, s61
	s_nop 0
	global_load_lds_dwordx4 v[236:237], off
	s_waitcnt vmcnt(8)
	s_waitcnt lgkmcnt(0)
	s_setprio 1
	s_barrier
	v_mfma_f32_16x16x32_bf16 v[62:65], v[136:139], v[186:189], v[62:65]
	v_mfma_f32_16x16x32_bf16 v[58:61], v[158:161], v[186:189], v[58:61]
	v_mfma_f32_16x16x32_bf16 v[50:53], v[136:139], v[194:197], v[50:53]
	v_mfma_f32_16x16x32_bf16 v[42:45], v[158:161], v[194:197], v[42:45]
	v_mfma_f32_16x16x32_bf16 v[34:37], v[136:139], v[214:217], v[34:37]
	v_mfma_f32_16x16x32_bf16 v[26:29], v[158:161], v[214:217], v[26:29]
	v_mfma_f32_16x16x32_bf16 v[18:21], v[136:139], v[222:225], v[18:21]
	v_mfma_f32_16x16x32_bf16 v[10:13], v[158:161], v[222:225], v[10:13]
	v_mfma_f32_16x16x32_bf16 v[62:65], v[140:143], v[190:193], v[62:65]
	v_mfma_f32_16x16x32_bf16 v[58:61], v[162:165], v[190:193], v[58:61]
	v_mfma_f32_16x16x32_bf16 v[50:53], v[140:143], v[210:213], v[50:53]
	v_mfma_f32_16x16x32_bf16 v[42:45], v[162:165], v[210:213], v[42:45]
	v_mfma_f32_16x16x32_bf16 v[34:37], v[140:143], v[218:221], v[34:37]
	v_mfma_f32_16x16x32_bf16 v[26:29], v[162:165], v[218:221], v[26:29]
	v_mfma_f32_16x16x32_bf16 v[18:21], v[140:143], v[226:229], v[18:21]
	v_mfma_f32_16x16x32_bf16 v[10:13], v[162:165], v[226:229], v[10:13]
	v_mfma_f32_16x16x32_bf16 v[54:57], v[170:173], v[186:189], v[54:57]
	v_mfma_f32_16x16x32_bf16 v[46:49], v[178:181], v[186:189], v[46:49]
	v_mfma_f32_16x16x32_bf16 v[38:41], v[170:173], v[194:197], v[38:41]
	v_mfma_f32_16x16x32_bf16 v[30:33], v[178:181], v[194:197], v[30:33]
	v_mfma_f32_16x16x32_bf16 v[22:25], v[170:173], v[214:217], v[22:25]
	v_mfma_f32_16x16x32_bf16 v[14:17], v[178:181], v[214:217], v[14:17]
	v_mfma_f32_16x16x32_bf16 v[6:9], v[170:173], v[222:225], v[6:9]
	v_mfma_f32_16x16x32_bf16 v[2:5], v[178:181], v[222:225], v[2:5]
	v_mfma_f32_16x16x32_bf16 v[54:57], v[174:177], v[190:193], v[54:57]
	v_mfma_f32_16x16x32_bf16 v[46:49], v[182:185], v[190:193], v[46:49]
	v_mfma_f32_16x16x32_bf16 v[38:41], v[174:177], v[210:213], v[38:41]
	v_mfma_f32_16x16x32_bf16 v[30:33], v[182:185], v[210:213], v[30:33]
	v_mfma_f32_16x16x32_bf16 v[22:25], v[174:177], v[218:221], v[22:25]
	v_mfma_f32_16x16x32_bf16 v[14:17], v[182:185], v[218:221], v[14:17]
	v_mfma_f32_16x16x32_bf16 v[6:9], v[174:177], v[226:229], v[6:9]
	v_mfma_f32_16x16x32_bf16 v[2:5], v[182:185], v[226:229], v[2:5]
	s_barrier
	s_setprio 0
	s_add_i32 s12, 0, 0x18000
	v_add_u32_e32 v114, s12, v119
	s_add_i32 s13, 0, 0x1c000
	ds_read_b128 v[136:139], v114
	ds_read_b128 v[140:143], v114 offset:1024
	ds_read_b128 v[158:161], v114 offset:2048
	ds_read_b128 v[162:165], v114 offset:3072
	v_add_u32_e32 v114, s13, v119
	ds_read_b128 v[170:173], v114
	ds_read_b128 v[174:177], v114 offset:1024
	ds_read_b128 v[178:181], v114 offset:2048
	ds_read_b128 v[182:185], v114 offset:3072
	s_add_u32 s10, s52, 0x20000
	s_addc_u32 s11, s53, 0
	s_mov_b32 m0, s62
	v_lshl_add_u64 v[238:239], s[10:11], 0, v[116:117]
	ds_read_b128 v[186:189], v169 offset:32768
	ds_read_b128 v[190:193], v169 offset:33792
	ds_read_b128 v[194:197], v169 offset:34816
	ds_read_b128 v[210:213], v169 offset:35840
	ds_read_b128 v[214:217], v169 offset:36864
	ds_read_b128 v[218:221], v169 offset:37888
	ds_read_b128 v[222:225], v169 offset:38912
	ds_read_b128 v[226:229], v169 offset:39936
	global_load_lds_dwordx4 v[238:239], off
	v_lshl_add_u64 v[238:239], s[10:11], 0, v[146:147]
	s_mov_b32 m0, s63
	s_nop 0
	global_load_lds_dwordx4 v[238:239], off
	s_waitcnt vmcnt(8)
	s_waitcnt lgkmcnt(0)
	s_setprio 1
	s_barrier
	v_mfma_f32_16x16x32_bf16 v[132:135], v[136:139], v[186:189], v[132:135]
	v_mfma_f32_16x16x32_bf16 v[128:131], v[158:161], v[186:189], v[128:131]
	v_mfma_f32_16x16x32_bf16 v[110:113], v[136:139], v[194:197], v[110:113]
	v_mfma_f32_16x16x32_bf16 v[106:109], v[158:161], v[194:197], v[106:109]
	v_mfma_f32_16x16x32_bf16 v[94:97], v[136:139], v[214:217], v[94:97]
	v_mfma_f32_16x16x32_bf16 v[90:93], v[158:161], v[214:217], v[90:93]
	v_mfma_f32_16x16x32_bf16 v[78:81], v[136:139], v[222:225], v[78:81]
	v_mfma_f32_16x16x32_bf16 v[74:77], v[158:161], v[222:225], v[74:77]
	v_mfma_f32_16x16x32_bf16 v[132:135], v[140:143], v[190:193], v[132:135]
	v_mfma_f32_16x16x32_bf16 v[128:131], v[162:165], v[190:193], v[128:131]
	v_mfma_f32_16x16x32_bf16 v[110:113], v[140:143], v[210:213], v[110:113]
	v_mfma_f32_16x16x32_bf16 v[106:109], v[162:165], v[210:213], v[106:109]
	v_mfma_f32_16x16x32_bf16 v[94:97], v[140:143], v[218:221], v[94:97]
	v_mfma_f32_16x16x32_bf16 v[90:93], v[162:165], v[218:221], v[90:93]
	v_mfma_f32_16x16x32_bf16 v[78:81], v[140:143], v[226:229], v[78:81]
	v_mfma_f32_16x16x32_bf16 v[74:77], v[162:165], v[226:229], v[74:77]
	v_mfma_f32_16x16x32_bf16 v[124:127], v[170:173], v[186:189], v[124:127]
	v_mfma_f32_16x16x32_bf16 v[120:123], v[178:181], v[186:189], v[120:123]
	v_mfma_f32_16x16x32_bf16 v[102:105], v[170:173], v[194:197], v[102:105]
	v_mfma_f32_16x16x32_bf16 v[98:101], v[178:181], v[194:197], v[98:101]
	v_mfma_f32_16x16x32_bf16 v[86:89], v[170:173], v[214:217], v[86:89]
	v_mfma_f32_16x16x32_bf16 v[82:85], v[178:181], v[214:217], v[82:85]
	v_mfma_f32_16x16x32_bf16 v[70:73], v[170:173], v[222:225], v[70:73]
	v_mfma_f32_16x16x32_bf16 v[66:69], v[178:181], v[222:225], v[66:69]
	v_mfma_f32_16x16x32_bf16 v[124:127], v[174:177], v[190:193], v[124:127]
	v_mfma_f32_16x16x32_bf16 v[120:123], v[182:185], v[190:193], v[120:123]
	v_mfma_f32_16x16x32_bf16 v[102:105], v[174:177], v[210:213], v[102:105]
	v_mfma_f32_16x16x32_bf16 v[98:101], v[182:185], v[210:213], v[98:101]
	v_mfma_f32_16x16x32_bf16 v[86:89], v[174:177], v[218:221], v[86:89]
	v_mfma_f32_16x16x32_bf16 v[82:85], v[182:185], v[218:221], v[82:85]
	v_mfma_f32_16x16x32_bf16 v[70:73], v[174:177], v[226:229], v[70:73]
	v_mfma_f32_16x16x32_bf16 v[66:69], v[182:185], v[226:229], v[66:69]
	s_barrier
	s_setprio 0
	s_add_i32 s10, s12, s60
	v_lshl_add_u64 v[166:167], v[166:167], 0, s[20:21]
	s_mov_b32 m0, s10
	ds_read_b128 v[186:189], v169 offset:49152
	ds_read_b128 v[190:193], v169 offset:50176
	ds_read_b128 v[194:197], v169 offset:51200
	ds_read_b128 v[210:213], v169 offset:52224
	ds_read_b128 v[214:217], v169 offset:53248
	ds_read_b128 v[218:221], v169 offset:54272
	ds_read_b128 v[222:225], v169 offset:55296
	ds_read_b128 v[226:229], v169 offset:56320
	global_load_lds_dwordx4 v[166:167], off
	s_add_i32 m0, s10, 0x2000
	s_add_u32 s10, s50, 0x20080
	v_lshl_add_u64 v[166:167], v[198:199], 0, s[20:21]
	s_addc_u32 s11, s51, 0
	s_add_i32 s12, s13, s60
	global_load_lds_dwordx4 v[166:167], off
	v_lshl_add_u64 v[166:167], s[10:11], 0, v[144:145]
	s_mov_b32 m0, s12
	s_nop 0
	global_load_lds_dwordx4 v[166:167], off
	v_lshl_add_u64 v[166:167], s[10:11], 0, v[148:149]
	s_add_i32 m0, s12, 0x2000
	s_nop 0
	global_load_lds_dwordx4 v[166:167], off
	v_lshl_add_u64 v[166:167], v[202:203], 0, s[20:21]
	s_mov_b32 m0, s64
	s_nop 0
	global_load_lds_dwordx4 v[166:167], off
	v_lshl_add_u64 v[166:167], v[236:237], 0, s[20:21]
	s_mov_b32 m0, s65
	s_nop 0
	global_load_lds_dwordx4 v[166:167], off
	s_waitcnt vmcnt(8)
	s_waitcnt lgkmcnt(0)
	s_setprio 1
	s_barrier
	v_mfma_f32_16x16x32_bf16 v[62:65], v[136:139], v[186:189], v[62:65]
	v_mfma_f32_16x16x32_bf16 v[58:61], v[158:161], v[186:189], v[58:61]
	v_mfma_f32_16x16x32_bf16 v[50:53], v[136:139], v[194:197], v[50:53]
	v_mfma_f32_16x16x32_bf16 v[42:45], v[158:161], v[194:197], v[42:45]
	v_mfma_f32_16x16x32_bf16 v[34:37], v[136:139], v[214:217], v[34:37]
	v_mfma_f32_16x16x32_bf16 v[26:29], v[158:161], v[214:217], v[26:29]
	v_mfma_f32_16x16x32_bf16 v[18:21], v[136:139], v[222:225], v[18:21]
	v_mfma_f32_16x16x32_bf16 v[10:13], v[158:161], v[222:225], v[10:13]
	v_mfma_f32_16x16x32_bf16 v[62:65], v[140:143], v[190:193], v[62:65]
	v_mfma_f32_16x16x32_bf16 v[58:61], v[162:165], v[190:193], v[58:61]
	v_mfma_f32_16x16x32_bf16 v[50:53], v[140:143], v[210:213], v[50:53]
	v_mfma_f32_16x16x32_bf16 v[42:45], v[162:165], v[210:213], v[42:45]
	v_mfma_f32_16x16x32_bf16 v[34:37], v[140:143], v[218:221], v[34:37]
	v_mfma_f32_16x16x32_bf16 v[26:29], v[162:165], v[218:221], v[26:29]
	v_mfma_f32_16x16x32_bf16 v[18:21], v[140:143], v[226:229], v[18:21]
	v_mfma_f32_16x16x32_bf16 v[10:13], v[162:165], v[226:229], v[10:13]
	v_mfma_f32_16x16x32_bf16 v[54:57], v[170:173], v[186:189], v[54:57]
	v_mfma_f32_16x16x32_bf16 v[46:49], v[178:181], v[186:189], v[46:49]
	v_mfma_f32_16x16x32_bf16 v[38:41], v[170:173], v[194:197], v[38:41]
	v_mfma_f32_16x16x32_bf16 v[30:33], v[178:181], v[194:197], v[30:33]
	v_mfma_f32_16x16x32_bf16 v[22:25], v[170:173], v[214:217], v[22:25]
	v_mfma_f32_16x16x32_bf16 v[14:17], v[178:181], v[214:217], v[14:17]
	v_mfma_f32_16x16x32_bf16 v[6:9], v[170:173], v[222:225], v[6:9]
	v_mfma_f32_16x16x32_bf16 v[2:5], v[178:181], v[222:225], v[2:5]
	v_mfma_f32_16x16x32_bf16 v[54:57], v[174:177], v[190:193], v[54:57]
	v_mfma_f32_16x16x32_bf16 v[46:49], v[182:185], v[190:193], v[46:49]
	v_mfma_f32_16x16x32_bf16 v[38:41], v[174:177], v[210:213], v[38:41]
	v_mfma_f32_16x16x32_bf16 v[30:33], v[182:185], v[210:213], v[30:33]
	v_mfma_f32_16x16x32_bf16 v[22:25], v[174:177], v[218:221], v[22:25]
	v_mfma_f32_16x16x32_bf16 v[14:17], v[182:185], v[218:221], v[14:17]
	v_mfma_f32_16x16x32_bf16 v[6:9], v[174:177], v[226:229], v[6:9]
	v_mfma_f32_16x16x32_bf16 v[2:5], v[182:185], v[226:229], v[2:5]
	s_barrier
	s_setprio 0
	s_add_i32 s9, s9, 2
	s_add_u32 s48, s48, 0x100
	s_addc_u32 s49, s49, 0
	s_add_u32 s7, s7, 0x100
	s_addc_u32 s8, s8, 0
	s_cmp_gt_u32 s9, 5
	s_cbranch_scc0 .LBB0_514
	s_and_b64 vcc, exec, s[26:27]
	s_cbranch_vccz .LBB0_517
	s_barrier

.LBB0_883:
	s_add_i32 s10, s11, 2
	s_add_u32 s12, s0, 0xfff00080
	s_addc_u32 s13, s1, -1
	s_add_i32 s14, 0, 0x10000
	s_cmp_eq_u32 s7, s11
	s_cselect_b32 s27, s3, s13
	s_cselect_b32 s26, s4, s12
	v_add_u32_e32 v114, s14, v119
	s_cselect_b32 s25, s5, s9
	s_cselect_b32 s24, s6, s8
	s_add_i32 s11, 0, 0x14000
	s_waitcnt lgkmcnt(0)
	ds_read_b128 v[136:139], v114
	ds_read_b128 v[140:143], v114 offset:1024
	ds_read_b128 v[158:161], v114 offset:2048
	ds_read_b128 v[162:165], v114 offset:3072
	v_add_u32_e32 v114, s11, v119
	ds_read_b128 v[166:169], v114
	ds_read_b128 v[170:173], v114 offset:1024
	ds_read_b128 v[174:177], v114 offset:2048
	ds_read_b128 v[180:183], v114 offset:3072
	v_lshl_add_u64 v[116:117], s[0:1], 0, v[154:155]
	s_add_i32 m0, s47, 0xc000
	ds_read_b128 v[184:187], v179
	ds_read_b128 v[188:191], v179 offset:1024
	ds_read_b128 v[192:195], v179 offset:2048
	ds_read_b128 v[196:199], v179 offset:3072
	ds_read_b128 v[210:213], v179 offset:4096
	ds_read_b128 v[214:217], v179 offset:5120
	ds_read_b128 v[218:221], v179 offset:6144
	ds_read_b128 v[222:225], v179 offset:7168
	global_load_lds_dwordx4 v[116:117], off
	v_lshl_add_u64 v[116:117], s[0:1], 0, v[156:157]
	s_add_i32 m0, s47, 0xe000
	s_nop 0
	global_load_lds_dwordx4 v[116:117], off
	s_waitcnt vmcnt(8)
	s_waitcnt lgkmcnt(0)
	s_setprio 1
	s_barrier
	v_mfma_f32_16x16x32_bf16 v[132:135], v[136:139], v[184:187], v[132:135]
	v_mfma_f32_16x16x32_bf16 v[128:131], v[158:161], v[184:187], v[128:131]
	v_mfma_f32_16x16x32_bf16 v[124:127], v[136:139], v[192:195], v[124:127]
	v_mfma_f32_16x16x32_bf16 v[120:123], v[158:161], v[192:195], v[120:123]
	v_mfma_f32_16x16x32_bf16 v[110:113], v[136:139], v[210:213], v[110:113]
	v_mfma_f32_16x16x32_bf16 v[106:109], v[158:161], v[210:213], v[106:109]
	v_mfma_f32_16x16x32_bf16 v[102:105], v[136:139], v[218:221], v[102:105]
	v_mfma_f32_16x16x32_bf16 v[98:101], v[158:161], v[218:221], v[98:101]
	v_mfma_f32_16x16x32_bf16 v[132:135], v[140:143], v[188:191], v[132:135]
	v_mfma_f32_16x16x32_bf16 v[128:131], v[162:165], v[188:191], v[128:131]
	v_mfma_f32_16x16x32_bf16 v[124:127], v[140:143], v[196:199], v[124:127]
	v_mfma_f32_16x16x32_bf16 v[120:123], v[162:165], v[196:199], v[120:123]
	v_mfma_f32_16x16x32_bf16 v[110:113], v[140:143], v[214:217], v[110:113]
	v_mfma_f32_16x16x32_bf16 v[106:109], v[162:165], v[214:217], v[106:109]
	v_mfma_f32_16x16x32_bf16 v[102:105], v[140:143], v[222:225], v[102:105]
	v_mfma_f32_16x16x32_bf16 v[98:101], v[162:165], v[222:225], v[98:101]
	v_mfma_f32_16x16x32_bf16 v[94:97], v[166:169], v[184:187], v[94:97]
	v_mfma_f32_16x16x32_bf16 v[90:93], v[174:177], v[184:187], v[90:93]
	v_mfma_f32_16x16x32_bf16 v[86:89], v[166:169], v[192:195], v[86:89]
	v_mfma_f32_16x16x32_bf16 v[82:85], v[174:177], v[192:195], v[82:85]
	v_mfma_f32_16x16x32_bf16 v[78:81], v[166:169], v[210:213], v[78:81]
	v_mfma_f32_16x16x32_bf16 v[74:77], v[174:177], v[210:213], v[74:77]
	v_mfma_f32_16x16x32_bf16 v[70:73], v[166:169], v[218:221], v[70:73]
	v_mfma_f32_16x16x32_bf16 v[66:69], v[174:177], v[218:221], v[66:69]
	v_mfma_f32_16x16x32_bf16 v[94:97], v[170:173], v[188:191], v[94:97]
	v_mfma_f32_16x16x32_bf16 v[90:93], v[180:183], v[188:191], v[90:93]
	v_mfma_f32_16x16x32_bf16 v[86:89], v[170:173], v[196:199], v[86:89]
	v_mfma_f32_16x16x32_bf16 v[82:85], v[180:183], v[196:199], v[82:85]
	v_mfma_f32_16x16x32_bf16 v[78:81], v[170:173], v[214:217], v[78:81]
	v_mfma_f32_16x16x32_bf16 v[74:77], v[180:183], v[214:217], v[74:77]
	v_mfma_f32_16x16x32_bf16 v[70:73], v[170:173], v[222:225], v[70:73]
	v_mfma_f32_16x16x32_bf16 v[66:69], v[180:183], v[222:225], v[66:69]
	s_barrier
	s_setprio 0
	s_add_i32 s12, s14, s75
	v_lshl_add_u64 v[116:117], s[24:25], 0, v[146:147]
	s_mov_b32 m0, s12
	ds_read_b128 v[184:187], v179 offset:16384
	ds_read_b128 v[188:191], v179 offset:17408
	ds_read_b128 v[192:195], v179 offset:18432
	ds_read_b128 v[196:199], v179 offset:19456
	ds_read_b128 v[210:213], v179 offset:20480
	ds_read_b128 v[214:217], v179 offset:21504
	ds_read_b128 v[218:221], v179 offset:22528
	ds_read_b128 v[222:225], v179 offset:23552
	global_load_lds_dwordx4 v[116:117], off
	s_add_i32 m0, s12, 0x2000
	s_add_u32 s12, s24, 0x100000
	v_lshl_add_u64 v[202:203], s[24:25], 0, v[150:151]
	s_addc_u32 s13, s25, 0
	s_add_i32 s11, s11, s75
	global_load_lds_dwordx4 v[202:203], off
	v_lshl_add_u64 v[226:227], s[12:13], 0, v[146:147]
	s_mov_b32 m0, s11
	v_lshl_add_u64 v[228:229], s[26:27], 0, v[148:149]
	global_load_lds_dwordx4 v[226:227], off
	v_lshl_add_u64 v[226:227], s[12:13], 0, v[150:151]
	s_add_i32 m0, s11, 0x2000
	s_nop 0
	global_load_lds_dwordx4 v[226:227], off
	v_lshl_add_u64 v[226:227], s[26:27], 0, v[144:145]
	s_mov_b32 m0, s47
	s_nop 0
	global_load_lds_dwordx4 v[226:227], off
	s_mov_b32 m0, s80
	s_nop 0
	global_load_lds_dwordx4 v[228:229], off
	s_waitcnt vmcnt(8)
	s_waitcnt lgkmcnt(0)
	s_setprio 1
	s_barrier
	v_mfma_f32_16x16x32_bf16 v[62:65], v[136:139], v[184:187], v[62:65]
	v_mfma_f32_16x16x32_bf16 v[58:61], v[158:161], v[184:187], v[58:61]
	v_mfma_f32_16x16x32_bf16 v[54:57], v[136:139], v[192:195], v[54:57]
	v_mfma_f32_16x16x32_bf16 v[50:53], v[158:161], v[192:195], v[50:53]
	v_mfma_f32_16x16x32_bf16 v[46:49], v[136:139], v[210:213], v[46:49]
	v_mfma_f32_16x16x32_bf16 v[42:45], v[158:161], v[210:213], v[42:45]
	v_mfma_f32_16x16x32_bf16 v[38:41], v[136:139], v[218:221], v[38:41]
	v_mfma_f32_16x16x32_bf16 v[34:37], v[158:161], v[218:221], v[34:37]
	v_mfma_f32_16x16x32_bf16 v[62:65], v[140:143], v[188:191], v[62:65]
	v_mfma_f32_16x16x32_bf16 v[58:61], v[162:165], v[188:191], v[58:61]
	v_mfma_f32_16x16x32_bf16 v[54:57], v[140:143], v[196:199], v[54:57]
	v_mfma_f32_16x16x32_bf16 v[50:53], v[162:165], v[196:199], v[50:53]
	v_mfma_f32_16x16x32_bf16 v[46:49], v[140:143], v[214:217], v[46:49]
	v_mfma_f32_16x16x32_bf16 v[42:45], v[162:165], v[214:217], v[42:45]
	v_mfma_f32_16x16x32_bf16 v[38:41], v[140:143], v[222:225], v[38:41]
	v_mfma_f32_16x16x32_bf16 v[34:37], v[162:165], v[222:225], v[34:37]
	v_mfma_f32_16x16x32_bf16 v[30:33], v[166:169], v[184:187], v[30:33]
	v_mfma_f32_16x16x32_bf16 v[26:29], v[174:177], v[184:187], v[26:29]
	v_mfma_f32_16x16x32_bf16 v[22:25], v[166:169], v[192:195], v[22:25]
	v_mfma_f32_16x16x32_bf16 v[18:21], v[174:177], v[192:195], v[18:21]
	v_mfma_f32_16x16x32_bf16 v[14:17], v[166:169], v[210:213], v[14:17]
	v_mfma_f32_16x16x32_bf16 v[10:13], v[174:177], v[210:213], v[10:13]
	v_mfma_f32_16x16x32_bf16 v[6:9], v[166:169], v[218:221], v[6:9]
	v_mfma_f32_16x16x32_bf16 v[2:5], v[174:177], v[218:221], v[2:5]
	v_mfma_f32_16x16x32_bf16 v[30:33], v[170:173], v[188:191], v[30:33]
	v_mfma_f32_16x16x32_bf16 v[26:29], v[180:183], v[188:191], v[26:29]
	v_mfma_f32_16x16x32_bf16 v[22:25], v[170:173], v[196:199], v[22:25]
	v_mfma_f32_16x16x32_bf16 v[18:21], v[180:183], v[196:199], v[18:21]
	v_mfma_f32_16x16x32_bf16 v[14:17], v[170:173], v[214:217], v[14:17]
	v_mfma_f32_16x16x32_bf16 v[10:13], v[180:183], v[214:217], v[10:13]
	v_mfma_f32_16x16x32_bf16 v[6:9], v[170:173], v[222:225], v[6:9]
	v_mfma_f32_16x16x32_bf16 v[2:5], v[180:183], v[222:225], v[2:5]
	s_barrier
	s_setprio 0
	s_add_i32 s11, 0, 0x18000
	v_add_u32_e32 v114, s11, v119
	s_add_i32 s14, 0, 0x1c000
	ds_read_b128 v[136:139], v114
	ds_read_b128 v[140:143], v114 offset:1024
	ds_read_b128 v[158:161], v114 offset:2048
	ds_read_b128 v[162:165], v114 offset:3072
	v_add_u32_e32 v114, s14, v119
	ds_read_b128 v[166:169], v114
	ds_read_b128 v[170:173], v114 offset:1024
	ds_read_b128 v[174:177], v114 offset:2048
	ds_read_b128 v[180:183], v114 offset:3072
	s_add_u32 s12, s26, 0x100000
	s_addc_u32 s13, s27, 0
	s_mov_b32 m0, s81
	v_lshl_add_u64 v[236:237], s[12:13], 0, v[144:145]
	ds_read_b128 v[184:187], v179 offset:32768
	ds_read_b128 v[188:191], v179 offset:33792
	ds_read_b128 v[192:195], v179 offset:34816
	ds_read_b128 v[196:199], v179 offset:35840
	ds_read_b128 v[210:213], v179 offset:36864
	ds_read_b128 v[214:217], v179 offset:37888
	ds_read_b128 v[218:221], v179 offset:38912
	ds_read_b128 v[222:225], v179 offset:39936
	global_load_lds_dwordx4 v[236:237], off
	v_lshl_add_u64 v[236:237], s[12:13], 0, v[148:149]
	s_mov_b32 m0, s82
	s_nop 0
	global_load_lds_dwordx4 v[236:237], off
	s_waitcnt vmcnt(8)
	s_waitcnt lgkmcnt(0)
	s_setprio 1
	s_barrier
	v_mfma_f32_16x16x32_bf16 v[132:135], v[136:139], v[184:187], v[132:135]
	v_mfma_f32_16x16x32_bf16 v[128:131], v[158:161], v[184:187], v[128:131]
	v_mfma_f32_16x16x32_bf16 v[124:127], v[136:139], v[192:195], v[124:127]
	v_mfma_f32_16x16x32_bf16 v[120:123], v[158:161], v[192:195], v[120:123]
	v_mfma_f32_16x16x32_bf16 v[110:113], v[136:139], v[210:213], v[110:113]
	v_mfma_f32_16x16x32_bf16 v[106:109], v[158:161], v[210:213], v[106:109]
	v_mfma_f32_16x16x32_bf16 v[102:105], v[136:139], v[218:221], v[102:105]
	v_mfma_f32_16x16x32_bf16 v[98:101], v[158:161], v[218:221], v[98:101]
	v_mfma_f32_16x16x32_bf16 v[132:135], v[140:143], v[188:191], v[132:135]
	v_mfma_f32_16x16x32_bf16 v[128:131], v[162:165], v[188:191], v[128:131]
	v_mfma_f32_16x16x32_bf16 v[124:127], v[140:143], v[196:199], v[124:127]
	v_mfma_f32_16x16x32_bf16 v[120:123], v[162:165], v[196:199], v[120:123]
	v_mfma_f32_16x16x32_bf16 v[110:113], v[140:143], v[214:217], v[110:113]
	v_mfma_f32_16x16x32_bf16 v[106:109], v[162:165], v[214:217], v[106:109]
	v_mfma_f32_16x16x32_bf16 v[102:105], v[140:143], v[222:225], v[102:105]
	v_mfma_f32_16x16x32_bf16 v[98:101], v[162:165], v[222:225], v[98:101]
	v_mfma_f32_16x16x32_bf16 v[94:97], v[166:169], v[184:187], v[94:97]
	v_mfma_f32_16x16x32_bf16 v[90:93], v[174:177], v[184:187], v[90:93]
	v_mfma_f32_16x16x32_bf16 v[86:89], v[166:169], v[192:195], v[86:89]
	v_mfma_f32_16x16x32_bf16 v[82:85], v[174:177], v[192:195], v[82:85]
	v_mfma_f32_16x16x32_bf16 v[78:81], v[166:169], v[210:213], v[78:81]
	v_mfma_f32_16x16x32_bf16 v[74:77], v[174:177], v[210:213], v[74:77]
	v_mfma_f32_16x16x32_bf16 v[70:73], v[166:169], v[218:221], v[70:73]
	v_mfma_f32_16x16x32_bf16 v[66:69], v[174:177], v[218:221], v[66:69]
	v_mfma_f32_16x16x32_bf16 v[94:97], v[170:173], v[188:191], v[94:97]
	v_mfma_f32_16x16x32_bf16 v[90:93], v[180:183], v[188:191], v[90:93]
	v_mfma_f32_16x16x32_bf16 v[86:89], v[170:173], v[196:199], v[86:89]
	v_mfma_f32_16x16x32_bf16 v[82:85], v[180:183], v[196:199], v[82:85]
	v_mfma_f32_16x16x32_bf16 v[78:81], v[170:173], v[214:217], v[78:81]
	v_mfma_f32_16x16x32_bf16 v[74:77], v[180:183], v[214:217], v[74:77]
	v_mfma_f32_16x16x32_bf16 v[70:73], v[170:173], v[222:225], v[70:73]
	v_mfma_f32_16x16x32_bf16 v[66:69], v[180:183], v[222:225], v[66:69]
	s_barrier
	s_setprio 0
	s_add_i32 s11, s11, s75
	v_lshl_add_u64 v[116:117], v[116:117], 0, s[20:21]
	s_mov_b32 m0, s11
	ds_read_b128 v[184:187], v179 offset:49152
	ds_read_b128 v[188:191], v179 offset:50176
	ds_read_b128 v[192:195], v179 offset:51200
	ds_read_b128 v[196:199], v179 offset:52224
	ds_read_b128 v[210:213], v179 offset:53248
	ds_read_b128 v[214:217], v179 offset:54272
	ds_read_b128 v[218:221], v179 offset:55296
	ds_read_b128 v[222:225], v179 offset:56320
	global_load_lds_dwordx4 v[116:117], off
	s_add_i32 m0, s11, 0x2000
	s_add_u32 s12, s24, 0x100080
	v_lshl_add_u64 v[116:117], v[202:203], 0, s[20:21]
	s_addc_u32 s13, s25, 0
	s_add_i32 s11, s14, s75
	global_load_lds_dwordx4 v[116:117], off
	v_lshl_add_u64 v[116:117], s[12:13], 0, v[146:147]
	s_mov_b32 m0, s11
	s_nop 0
	global_load_lds_dwordx4 v[116:117], off
	v_lshl_add_u64 v[116:117], s[12:13], 0, v[150:151]
	s_add_i32 m0, s11, 0x2000
	s_nop 0
	global_load_lds_dwordx4 v[116:117], off
	v_lshl_add_u64 v[116:117], v[226:227], 0, s[20:21]
	s_mov_b32 m0, s83
	s_nop 0
	global_load_lds_dwordx4 v[116:117], off
	v_lshl_add_u64 v[116:117], v[228:229], 0, s[20:21]
	s_mov_b32 m0, s84
	s_nop 0
	global_load_lds_dwordx4 v[116:117], off
	s_waitcnt vmcnt(8)
	s_waitcnt lgkmcnt(0)
	s_setprio 1
	s_barrier
	v_mfma_f32_16x16x32_bf16 v[62:65], v[136:139], v[184:187], v[62:65]
	v_mfma_f32_16x16x32_bf16 v[58:61], v[158:161], v[184:187], v[58:61]
	v_mfma_f32_16x16x32_bf16 v[54:57], v[136:139], v[192:195], v[54:57]
	v_mfma_f32_16x16x32_bf16 v[50:53], v[158:161], v[192:195], v[50:53]
	v_mfma_f32_16x16x32_bf16 v[46:49], v[136:139], v[210:213], v[46:49]
	v_mfma_f32_16x16x32_bf16 v[42:45], v[158:161], v[210:213], v[42:45]
	v_mfma_f32_16x16x32_bf16 v[38:41], v[136:139], v[218:221], v[38:41]
	v_mfma_f32_16x16x32_bf16 v[34:37], v[158:161], v[218:221], v[34:37]
	v_mfma_f32_16x16x32_bf16 v[62:65], v[140:143], v[188:191], v[62:65]
	v_mfma_f32_16x16x32_bf16 v[58:61], v[162:165], v[188:191], v[58:61]
	v_mfma_f32_16x16x32_bf16 v[54:57], v[140:143], v[196:199], v[54:57]
	v_mfma_f32_16x16x32_bf16 v[50:53], v[162:165], v[196:199], v[50:53]
	v_mfma_f32_16x16x32_bf16 v[46:49], v[140:143], v[214:217], v[46:49]
	v_mfma_f32_16x16x32_bf16 v[42:45], v[162:165], v[214:217], v[42:45]
	v_mfma_f32_16x16x32_bf16 v[38:41], v[140:143], v[222:225], v[38:41]
	v_mfma_f32_16x16x32_bf16 v[34:37], v[162:165], v[222:225], v[34:37]
	v_mfma_f32_16x16x32_bf16 v[30:33], v[166:169], v[184:187], v[30:33]
	v_mfma_f32_16x16x32_bf16 v[26:29], v[174:177], v[184:187], v[26:29]
	v_mfma_f32_16x16x32_bf16 v[22:25], v[166:169], v[192:195], v[22:25]
	v_mfma_f32_16x16x32_bf16 v[18:21], v[174:177], v[192:195], v[18:21]
	v_mfma_f32_16x16x32_bf16 v[14:17], v[166:169], v[210:213], v[14:17]
	v_mfma_f32_16x16x32_bf16 v[10:13], v[174:177], v[210:213], v[10:13]
	v_mfma_f32_16x16x32_bf16 v[6:9], v[166:169], v[218:221], v[6:9]
	v_mfma_f32_16x16x32_bf16 v[2:5], v[174:177], v[218:221], v[2:5]
	v_mfma_f32_16x16x32_bf16 v[30:33], v[170:173], v[188:191], v[30:33]
	v_mfma_f32_16x16x32_bf16 v[26:29], v[180:183], v[188:191], v[26:29]
	v_mfma_f32_16x16x32_bf16 v[22:25], v[170:173], v[196:199], v[22:25]
	v_mfma_f32_16x16x32_bf16 v[18:21], v[180:183], v[196:199], v[18:21]
	v_mfma_f32_16x16x32_bf16 v[14:17], v[170:173], v[214:217], v[14:17]
	v_mfma_f32_16x16x32_bf16 v[10:13], v[180:183], v[214:217], v[10:13]
	v_mfma_f32_16x16x32_bf16 v[6:9], v[170:173], v[222:225], v[6:9]
	v_mfma_f32_16x16x32_bf16 v[2:5], v[180:183], v[222:225], v[2:5]
	s_barrier
	s_setprio 0
	s_add_u32 s0, s0, 0x100
	s_addc_u32 s1, s1, 0
	s_add_u32 s8, s8, 0x100
	s_addc_u32 s9, s9, 0
	s_cmp_ge_i32 s10, s89
	s_mov_b32 s11, s10
	s_cbranch_scc0 .LBB0_883

.LBB0_1166:
	s_add_u32 s10, s50, 0xfff00080
	s_addc_u32 s11, s51, -1
	s_add_i32 s12, 0, 0x10000
	s_cmp_eq_u32 s9, 60
	s_cselect_b32 s55, s1, s11
	s_cselect_b32 s54, s4, s10
	v_add_u32_e32 v156, s12, v158
	s_cselect_b32 s53, s5, s8
	s_cselect_b32 s52, s6, s7
	s_add_i32 s13, 0, 0x14000
	ds_read_b128 v[160:163], v156
	ds_read_b128 v[164:167], v156 offset:1024
	ds_read_b128 v[168:171], v156 offset:2048
	ds_read_b128 v[172:175], v156 offset:3072
	v_add_u32_e32 v156, s13, v158
	ds_read_b128 v[176:179], v156
	ds_read_b128 v[180:183], v156 offset:1024
	ds_read_b128 v[184:187], v156 offset:2048
	ds_read_b128 v[188:191], v156 offset:3072
	v_lshl_add_u64 v[156:157], s[50:51], 0, v[152:153]
	s_add_i32 m0, s65, 0xc000
	ds_read_b128 v[192:195], v159
	ds_read_b128 v[196:199], v159 offset:1024
	ds_read_b128 v[210:213], v159 offset:2048
	ds_read_b128 v[214:217], v159 offset:3072
	ds_read_b128 v[218:221], v159 offset:4096
	ds_read_b128 v[222:225], v159 offset:5120
	ds_read_b128 v[226:229], v159 offset:6144
	ds_read_b128 v[236:239], v159 offset:7168
	global_load_lds_dwordx4 v[156:157], off
	v_lshl_add_u64 v[156:157], s[50:51], 0, v[154:155]
	s_add_i32 m0, s65, 0xe000
	s_nop 0
	global_load_lds_dwordx4 v[156:157], off
	s_waitcnt vmcnt(8)
	s_waitcnt lgkmcnt(0)
	s_setprio 1
	s_barrier
	v_mfma_f32_16x16x32_bf16 v[132:135], v[160:163], v[192:195], v[132:135]
	v_mfma_f32_16x16x32_bf16 v[128:131], v[168:171], v[192:195], v[128:131]
	v_mfma_f32_16x16x32_bf16 v[110:113], v[160:163], v[210:213], v[110:113]
	v_mfma_f32_16x16x32_bf16 v[106:109], v[168:171], v[210:213], v[106:109]
	v_mfma_f32_16x16x32_bf16 v[94:97], v[160:163], v[218:221], v[94:97]
	v_mfma_f32_16x16x32_bf16 v[90:93], v[168:171], v[218:221], v[90:93]
	v_mfma_f32_16x16x32_bf16 v[78:81], v[160:163], v[226:229], v[78:81]
	v_mfma_f32_16x16x32_bf16 v[74:77], v[168:171], v[226:229], v[74:77]
	v_mfma_f32_16x16x32_bf16 v[132:135], v[164:167], v[196:199], v[132:135]
	v_mfma_f32_16x16x32_bf16 v[128:131], v[172:175], v[196:199], v[128:131]
	v_mfma_f32_16x16x32_bf16 v[110:113], v[164:167], v[214:217], v[110:113]
	v_mfma_f32_16x16x32_bf16 v[106:109], v[172:175], v[214:217], v[106:109]
	v_mfma_f32_16x16x32_bf16 v[94:97], v[164:167], v[222:225], v[94:97]
	v_mfma_f32_16x16x32_bf16 v[90:93], v[172:175], v[222:225], v[90:93]
	v_mfma_f32_16x16x32_bf16 v[78:81], v[164:167], v[236:239], v[78:81]
	v_mfma_f32_16x16x32_bf16 v[74:77], v[172:175], v[236:239], v[74:77]
	v_mfma_f32_16x16x32_bf16 v[124:127], v[176:179], v[192:195], v[124:127]
	v_mfma_f32_16x16x32_bf16 v[120:123], v[184:187], v[192:195], v[120:123]
	v_mfma_f32_16x16x32_bf16 v[102:105], v[176:179], v[210:213], v[102:105]
	v_mfma_f32_16x16x32_bf16 v[98:101], v[184:187], v[210:213], v[98:101]
	v_mfma_f32_16x16x32_bf16 v[86:89], v[176:179], v[218:221], v[86:89]
	v_mfma_f32_16x16x32_bf16 v[82:85], v[184:187], v[218:221], v[82:85]
	v_mfma_f32_16x16x32_bf16 v[70:73], v[176:179], v[226:229], v[70:73]
	v_mfma_f32_16x16x32_bf16 v[66:69], v[184:187], v[226:229], v[66:69]
	v_mfma_f32_16x16x32_bf16 v[124:127], v[180:183], v[196:199], v[124:127]
	v_mfma_f32_16x16x32_bf16 v[120:123], v[188:191], v[196:199], v[120:123]
	v_mfma_f32_16x16x32_bf16 v[102:105], v[180:183], v[214:217], v[102:105]
	v_mfma_f32_16x16x32_bf16 v[98:101], v[188:191], v[214:217], v[98:101]
	v_mfma_f32_16x16x32_bf16 v[86:89], v[180:183], v[222:225], v[86:89]
	v_mfma_f32_16x16x32_bf16 v[82:85], v[188:191], v[222:225], v[82:85]
	v_mfma_f32_16x16x32_bf16 v[70:73], v[180:183], v[236:239], v[70:73]
	v_mfma_f32_16x16x32_bf16 v[66:69], v[188:191], v[236:239], v[66:69]
	s_barrier
	s_setprio 0
	s_add_i32 s10, s12, s64
	v_lshl_add_u64 v[156:157], s[52:53], 0, v[136:137]
	s_mov_b32 m0, s10
	ds_read_b128 v[192:195], v159 offset:16384
	ds_read_b128 v[196:199], v159 offset:17408
	ds_read_b128 v[210:213], v159 offset:18432
	ds_read_b128 v[214:217], v159 offset:19456
	ds_read_b128 v[218:221], v159 offset:20480
	ds_read_b128 v[222:225], v159 offset:21504
	ds_read_b128 v[226:229], v159 offset:22528
	ds_read_b128 v[236:239], v159 offset:23552
	global_load_lds_dwordx4 v[156:157], off
	s_add_i32 m0, s10, 0x2000
	s_add_u32 s10, s52, 0x100000
	v_lshl_add_u64 v[202:203], s[52:53], 0, v[140:141]
	s_addc_u32 s11, s53, 0
	s_add_i32 s12, s13, s64
	global_load_lds_dwordx4 v[202:203], off
	v_lshl_add_u64 v[240:241], s[10:11], 0, v[136:137]
	s_mov_b32 m0, s12
	v_lshl_add_u64 v[242:243], s[54:55], 0, v[138:139]
	global_load_lds_dwordx4 v[240:241], off
	v_lshl_add_u64 v[240:241], s[10:11], 0, v[140:141]
	s_add_i32 m0, s12, 0x2000
	s_nop 0
	global_load_lds_dwordx4 v[240:241], off
	v_lshl_add_u64 v[240:241], s[54:55], 0, v[116:117]
	s_mov_b32 m0, s65
	s_nop 0
	global_load_lds_dwordx4 v[240:241], off
	s_mov_b32 m0, s66
	s_nop 0
	global_load_lds_dwordx4 v[242:243], off
	s_waitcnt vmcnt(8)
	s_waitcnt lgkmcnt(0)
	s_setprio 1
	s_barrier
	v_mfma_f32_16x16x32_bf16 v[62:65], v[160:163], v[192:195], v[62:65]
	v_mfma_f32_16x16x32_bf16 v[58:61], v[168:171], v[192:195], v[58:61]
	v_mfma_f32_16x16x32_bf16 v[46:49], v[160:163], v[210:213], v[46:49]
	v_mfma_f32_16x16x32_bf16 v[42:45], v[168:171], v[210:213], v[42:45]
	v_mfma_f32_16x16x32_bf16 v[30:33], v[160:163], v[218:221], v[30:33]
	v_mfma_f32_16x16x32_bf16 v[26:29], v[168:171], v[218:221], v[26:29]
	v_mfma_f32_16x16x32_bf16 v[14:17], v[160:163], v[226:229], v[14:17]
	v_mfma_f32_16x16x32_bf16 v[10:13], v[168:171], v[226:229], v[10:13]
	v_mfma_f32_16x16x32_bf16 v[62:65], v[164:167], v[196:199], v[62:65]
	v_mfma_f32_16x16x32_bf16 v[58:61], v[172:175], v[196:199], v[58:61]
	v_mfma_f32_16x16x32_bf16 v[46:49], v[164:167], v[214:217], v[46:49]
	v_mfma_f32_16x16x32_bf16 v[42:45], v[172:175], v[214:217], v[42:45]
	v_mfma_f32_16x16x32_bf16 v[30:33], v[164:167], v[222:225], v[30:33]
	v_mfma_f32_16x16x32_bf16 v[26:29], v[172:175], v[222:225], v[26:29]
	v_mfma_f32_16x16x32_bf16 v[14:17], v[164:167], v[236:239], v[14:17]
	v_mfma_f32_16x16x32_bf16 v[10:13], v[172:175], v[236:239], v[10:13]
	v_mfma_f32_16x16x32_bf16 v[54:57], v[176:179], v[192:195], v[54:57]
	v_mfma_f32_16x16x32_bf16 v[50:53], v[184:187], v[192:195], v[50:53]
	v_mfma_f32_16x16x32_bf16 v[38:41], v[176:179], v[210:213], v[38:41]
	v_mfma_f32_16x16x32_bf16 v[34:37], v[184:187], v[210:213], v[34:37]
	v_mfma_f32_16x16x32_bf16 v[22:25], v[176:179], v[218:221], v[22:25]
	v_mfma_f32_16x16x32_bf16 v[18:21], v[184:187], v[218:221], v[18:21]
	v_mfma_f32_16x16x32_bf16 v[6:9], v[176:179], v[226:229], v[6:9]
	v_mfma_f32_16x16x32_bf16 v[2:5], v[184:187], v[226:229], v[2:5]
	v_mfma_f32_16x16x32_bf16 v[54:57], v[180:183], v[196:199], v[54:57]
	v_mfma_f32_16x16x32_bf16 v[50:53], v[188:191], v[196:199], v[50:53]
	v_mfma_f32_16x16x32_bf16 v[38:41], v[180:183], v[214:217], v[38:41]
	v_mfma_f32_16x16x32_bf16 v[34:37], v[188:191], v[214:217], v[34:37]
	v_mfma_f32_16x16x32_bf16 v[22:25], v[180:183], v[222:225], v[22:25]
	v_mfma_f32_16x16x32_bf16 v[18:21], v[188:191], v[222:225], v[18:21]
	v_mfma_f32_16x16x32_bf16 v[6:9], v[180:183], v[236:239], v[6:9]
	v_mfma_f32_16x16x32_bf16 v[2:5], v[188:191], v[236:239], v[2:5]
	s_barrier
	s_setprio 0
	s_add_i32 s12, 0, 0x18000
	s_add_i32 s13, 0, 0x1c000
	v_add_u32_e32 v172, s12, v158
	v_add_u32_e32 v188, s13, v158
	ds_read_b128 v[160:163], v172
	ds_read_b128 v[164:167], v172 offset:1024
	ds_read_b128 v[168:171], v172 offset:2048
	ds_read_b128 v[172:175], v172 offset:3072
	ds_read_b128 v[176:179], v188
	ds_read_b128 v[180:183], v188 offset:1024
	ds_read_b128 v[184:187], v188 offset:2048
	ds_read_b128 v[188:191], v188 offset:3072
	s_add_u32 s10, s54, 0x100000
	s_addc_u32 s11, s55, 0
	s_mov_b32 m0, s67
	v_lshl_add_u64 v[244:245], s[10:11], 0, v[116:117]
	ds_read_b128 v[192:195], v159 offset:32768
	ds_read_b128 v[196:199], v159 offset:33792
	ds_read_b128 v[210:213], v159 offset:34816
	ds_read_b128 v[214:217], v159 offset:35840
	ds_read_b128 v[218:221], v159 offset:36864
	ds_read_b128 v[222:225], v159 offset:37888
	ds_read_b128 v[226:229], v159 offset:38912
	ds_read_b128 v[236:239], v159 offset:39936
	global_load_lds_dwordx4 v[244:245], off
	v_lshl_add_u64 v[244:245], s[10:11], 0, v[138:139]
	s_mov_b32 m0, s68
	s_nop 0
	global_load_lds_dwordx4 v[244:245], off
	s_waitcnt vmcnt(8)
	s_waitcnt lgkmcnt(0)
	s_setprio 1
	s_barrier
	v_mfma_f32_16x16x32_bf16 v[132:135], v[160:163], v[192:195], v[132:135]
	v_mfma_f32_16x16x32_bf16 v[128:131], v[168:171], v[192:195], v[128:131]
	v_mfma_f32_16x16x32_bf16 v[110:113], v[160:163], v[210:213], v[110:113]
	v_mfma_f32_16x16x32_bf16 v[106:109], v[168:171], v[210:213], v[106:109]
	v_mfma_f32_16x16x32_bf16 v[94:97], v[160:163], v[218:221], v[94:97]
	v_mfma_f32_16x16x32_bf16 v[90:93], v[168:171], v[218:221], v[90:93]
	v_mfma_f32_16x16x32_bf16 v[78:81], v[160:163], v[226:229], v[78:81]
	v_mfma_f32_16x16x32_bf16 v[74:77], v[168:171], v[226:229], v[74:77]
	v_mfma_f32_16x16x32_bf16 v[132:135], v[164:167], v[196:199], v[132:135]
	v_mfma_f32_16x16x32_bf16 v[128:131], v[172:175], v[196:199], v[128:131]
	v_mfma_f32_16x16x32_bf16 v[110:113], v[164:167], v[214:217], v[110:113]
	v_mfma_f32_16x16x32_bf16 v[106:109], v[172:175], v[214:217], v[106:109]
	v_mfma_f32_16x16x32_bf16 v[94:97], v[164:167], v[222:225], v[94:97]
	v_mfma_f32_16x16x32_bf16 v[90:93], v[172:175], v[222:225], v[90:93]
	v_mfma_f32_16x16x32_bf16 v[78:81], v[164:167], v[236:239], v[78:81]
	v_mfma_f32_16x16x32_bf16 v[74:77], v[172:175], v[236:239], v[74:77]
	v_mfma_f32_16x16x32_bf16 v[124:127], v[176:179], v[192:195], v[124:127]
	v_mfma_f32_16x16x32_bf16 v[120:123], v[184:187], v[192:195], v[120:123]
	v_mfma_f32_16x16x32_bf16 v[102:105], v[176:179], v[210:213], v[102:105]
	v_mfma_f32_16x16x32_bf16 v[98:101], v[184:187], v[210:213], v[98:101]
	v_mfma_f32_16x16x32_bf16 v[86:89], v[176:179], v[218:221], v[86:89]
	v_mfma_f32_16x16x32_bf16 v[82:85], v[184:187], v[218:221], v[82:85]
	v_mfma_f32_16x16x32_bf16 v[70:73], v[176:179], v[226:229], v[70:73]
	v_mfma_f32_16x16x32_bf16 v[66:69], v[184:187], v[226:229], v[66:69]
	v_mfma_f32_16x16x32_bf16 v[124:127], v[180:183], v[196:199], v[124:127]
	v_mfma_f32_16x16x32_bf16 v[120:123], v[188:191], v[196:199], v[120:123]
	v_mfma_f32_16x16x32_bf16 v[102:105], v[180:183], v[214:217], v[102:105]
	v_mfma_f32_16x16x32_bf16 v[98:101], v[188:191], v[214:217], v[98:101]
	v_mfma_f32_16x16x32_bf16 v[86:89], v[180:183], v[222:225], v[86:89]
	v_mfma_f32_16x16x32_bf16 v[82:85], v[188:191], v[222:225], v[82:85]
	v_mfma_f32_16x16x32_bf16 v[70:73], v[180:183], v[236:239], v[70:73]
	v_mfma_f32_16x16x32_bf16 v[66:69], v[188:191], v[236:239], v[66:69]
	s_barrier
	s_setprio 0
	s_add_i32 s10, s12, s64
	v_lshl_add_u64 v[156:157], v[156:157], 0, s[20:21]
	s_mov_b32 m0, s10
	ds_read_b128 v[192:195], v159 offset:49152
	ds_read_b128 v[196:199], v159 offset:50176
	ds_read_b128 v[210:213], v159 offset:51200
	ds_read_b128 v[214:217], v159 offset:52224
	ds_read_b128 v[218:221], v159 offset:53248
	ds_read_b128 v[222:225], v159 offset:54272
	ds_read_b128 v[226:229], v159 offset:55296
	ds_read_b128 v[236:239], v159 offset:56320
	global_load_lds_dwordx4 v[156:157], off
	s_add_i32 m0, s10, 0x2000
	s_add_u32 s10, s52, 0x100080
	v_lshl_add_u64 v[156:157], v[202:203], 0, s[20:21]
	s_addc_u32 s11, s53, 0
	s_add_i32 s12, s13, s64
	global_load_lds_dwordx4 v[156:157], off
	v_lshl_add_u64 v[156:157], s[10:11], 0, v[136:137]
	s_mov_b32 m0, s12
	s_nop 0
	global_load_lds_dwordx4 v[156:157], off
	v_lshl_add_u64 v[156:157], s[10:11], 0, v[140:141]
	s_add_i32 m0, s12, 0x2000
	s_nop 0
	global_load_lds_dwordx4 v[156:157], off
	v_lshl_add_u64 v[156:157], v[240:241], 0, s[20:21]
	s_mov_b32 m0, s71
	s_nop 0
	global_load_lds_dwordx4 v[156:157], off
	v_lshl_add_u64 v[156:157], v[242:243], 0, s[20:21]
	s_mov_b32 m0, s72
	s_nop 0
	global_load_lds_dwordx4 v[156:157], off
	s_waitcnt vmcnt(8)
	s_waitcnt lgkmcnt(0)
	s_setprio 1
	s_barrier
	v_mfma_f32_16x16x32_bf16 v[62:65], v[160:163], v[192:195], v[62:65]
	v_mfma_f32_16x16x32_bf16 v[58:61], v[168:171], v[192:195], v[58:61]
	v_mfma_f32_16x16x32_bf16 v[46:49], v[160:163], v[210:213], v[46:49]
	v_mfma_f32_16x16x32_bf16 v[42:45], v[168:171], v[210:213], v[42:45]
	v_mfma_f32_16x16x32_bf16 v[30:33], v[160:163], v[218:221], v[30:33]
	v_mfma_f32_16x16x32_bf16 v[26:29], v[168:171], v[218:221], v[26:29]
	v_mfma_f32_16x16x32_bf16 v[14:17], v[160:163], v[226:229], v[14:17]
	v_mfma_f32_16x16x32_bf16 v[10:13], v[168:171], v[226:229], v[10:13]
	v_mfma_f32_16x16x32_bf16 v[62:65], v[164:167], v[196:199], v[62:65]
	v_mfma_f32_16x16x32_bf16 v[58:61], v[172:175], v[196:199], v[58:61]
	v_mfma_f32_16x16x32_bf16 v[46:49], v[164:167], v[214:217], v[46:49]
	v_mfma_f32_16x16x32_bf16 v[42:45], v[172:175], v[214:217], v[42:45]
	v_mfma_f32_16x16x32_bf16 v[30:33], v[164:167], v[222:225], v[30:33]
	v_mfma_f32_16x16x32_bf16 v[26:29], v[172:175], v[222:225], v[26:29]
	v_mfma_f32_16x16x32_bf16 v[14:17], v[164:167], v[236:239], v[14:17]
	v_mfma_f32_16x16x32_bf16 v[10:13], v[172:175], v[236:239], v[10:13]
	v_mfma_f32_16x16x32_bf16 v[54:57], v[176:179], v[192:195], v[54:57]
	v_mfma_f32_16x16x32_bf16 v[50:53], v[184:187], v[192:195], v[50:53]
	v_mfma_f32_16x16x32_bf16 v[38:41], v[176:179], v[210:213], v[38:41]
	v_mfma_f32_16x16x32_bf16 v[34:37], v[184:187], v[210:213], v[34:37]
	v_mfma_f32_16x16x32_bf16 v[22:25], v[176:179], v[218:221], v[22:25]
	v_mfma_f32_16x16x32_bf16 v[18:21], v[184:187], v[218:221], v[18:21]
	v_mfma_f32_16x16x32_bf16 v[6:9], v[176:179], v[226:229], v[6:9]
	v_mfma_f32_16x16x32_bf16 v[2:5], v[184:187], v[226:229], v[2:5]
	v_mfma_f32_16x16x32_bf16 v[54:57], v[180:183], v[196:199], v[54:57]
	v_mfma_f32_16x16x32_bf16 v[50:53], v[188:191], v[196:199], v[50:53]
	v_mfma_f32_16x16x32_bf16 v[38:41], v[180:183], v[214:217], v[38:41]
	v_mfma_f32_16x16x32_bf16 v[34:37], v[188:191], v[214:217], v[34:37]
	v_mfma_f32_16x16x32_bf16 v[22:25], v[180:183], v[222:225], v[22:25]
	v_mfma_f32_16x16x32_bf16 v[18:21], v[188:191], v[222:225], v[18:21]
	v_mfma_f32_16x16x32_bf16 v[6:9], v[180:183], v[236:239], v[6:9]
	v_mfma_f32_16x16x32_bf16 v[2:5], v[188:191], v[236:239], v[2:5]
	s_barrier
	s_setprio 0
	s_add_i32 s9, s9, 2
	s_add_u32 s50, s50, 0x100
	s_addc_u32 s51, s51, 0
	s_add_u32 s7, s7, 0x100
	s_addc_u32 s8, s8, 0
	s_cmp_gt_u32 s9, 61
	s_cbranch_scc0 .LBB0_1166
	s_and_b64 vcc, exec, s[30:31]
	s_cbranch_vccz .LBB0_1169
	s_barrier

.LBB0_1372:
	s_add_i32 s15, s16, 2
	s_add_u32 s17, s40, 0x4000
	s_addc_u32 s18, s41, 0
	s_cmp_eq_u32 s12, s16
	s_cselect_b32 s82, s9, s17
	s_cselect_b32 s83, s8, s18
	s_cselect_b32 s80, s11, s13
	s_cselect_b32 s81, s10, s14
	s_add_u32 s78, s82, 0x8000
	s_addc_u32 s79, s83, 0
	s_add_i32 s16, 0, 0x10000
	v_add_u32_e32 v114, s16, v119
	s_add_i32 s18, 0, 0x14000
	ds_read_b128 v[136:139], v114
	ds_read_b128 v[140:143], v114 offset:1024
	ds_read_b128 v[170:173], v114 offset:2048
	ds_read_b128 v[174:177], v114 offset:3072
	v_add_u32_e32 v114, s18, v119
	ds_read_b128 v[178:181], v114
	ds_read_b128 v[182:185], v114 offset:1024
	ds_read_b128 v[186:189], v114 offset:2048
	ds_read_b128 v[190:193], v114 offset:3072
	s_waitcnt lgkmcnt(0)
	v_lshl_add_u64 v[116:117], s[40:41], 0, v[166:167]
	s_add_i32 m0, s23, 0xc000
	ds_read_b128 v[194:197], v153
	ds_read_b128 v[210:213], v153 offset:1024
	ds_read_b128 v[214:217], v153 offset:2048
	ds_read_b128 v[218:221], v153 offset:3072
	ds_read_b128 v[222:225], v153 offset:4096
	ds_read_b128 v[226:229], v153 offset:5120
	ds_read_b128 v[236:239], v153 offset:6144
	ds_read_b128 v[240:243], v153 offset:7168
	global_load_lds_dwordx4 v[116:117], off
	v_lshl_add_u64 v[116:117], s[40:41], 0, v[168:169]
	s_add_i32 m0, s23, 0xe000
	s_nop 0
	global_load_lds_dwordx4 v[116:117], off
	s_waitcnt vmcnt(8)
	s_waitcnt lgkmcnt(0)
	s_setprio 1
	s_barrier
	v_mfma_f32_16x16x32_bf16 v[132:135], v[136:139], v[194:197], v[132:135]
	v_mfma_f32_16x16x32_bf16 v[128:131], v[170:173], v[194:197], v[128:131]
	v_mfma_f32_16x16x32_bf16 v[124:127], v[136:139], v[214:217], v[124:127]
	v_mfma_f32_16x16x32_bf16 v[120:123], v[170:173], v[214:217], v[120:123]
	v_mfma_f32_16x16x32_bf16 v[110:113], v[136:139], v[222:225], v[110:113]
	v_mfma_f32_16x16x32_bf16 v[106:109], v[170:173], v[222:225], v[106:109]
	v_mfma_f32_16x16x32_bf16 v[102:105], v[136:139], v[236:239], v[102:105]
	v_mfma_f32_16x16x32_bf16 v[98:101], v[170:173], v[236:239], v[98:101]
	v_mfma_f32_16x16x32_bf16 v[132:135], v[140:143], v[210:213], v[132:135]
	v_mfma_f32_16x16x32_bf16 v[128:131], v[174:177], v[210:213], v[128:131]
	v_mfma_f32_16x16x32_bf16 v[124:127], v[140:143], v[218:221], v[124:127]
	v_mfma_f32_16x16x32_bf16 v[120:123], v[174:177], v[218:221], v[120:123]
	v_mfma_f32_16x16x32_bf16 v[110:113], v[140:143], v[226:229], v[110:113]
	v_mfma_f32_16x16x32_bf16 v[106:109], v[174:177], v[226:229], v[106:109]
	v_mfma_f32_16x16x32_bf16 v[102:105], v[140:143], v[240:243], v[102:105]
	v_mfma_f32_16x16x32_bf16 v[98:101], v[174:177], v[240:243], v[98:101]
	v_mfma_f32_16x16x32_bf16 v[94:97], v[178:181], v[194:197], v[94:97]
	v_mfma_f32_16x16x32_bf16 v[90:93], v[186:189], v[194:197], v[90:93]
	v_mfma_f32_16x16x32_bf16 v[86:89], v[178:181], v[214:217], v[86:89]
	v_mfma_f32_16x16x32_bf16 v[82:85], v[186:189], v[214:217], v[82:85]
	v_mfma_f32_16x16x32_bf16 v[78:81], v[178:181], v[222:225], v[78:81]
	v_mfma_f32_16x16x32_bf16 v[74:77], v[186:189], v[222:225], v[74:77]
	v_mfma_f32_16x16x32_bf16 v[66:69], v[178:181], v[236:239], v[66:69]
	v_mfma_f32_16x16x32_bf16 v[58:61], v[186:189], v[236:239], v[58:61]
	v_mfma_f32_16x16x32_bf16 v[94:97], v[182:185], v[210:213], v[94:97]
	v_mfma_f32_16x16x32_bf16 v[90:93], v[190:193], v[210:213], v[90:93]
	v_mfma_f32_16x16x32_bf16 v[86:89], v[182:185], v[218:221], v[86:89]
	v_mfma_f32_16x16x32_bf16 v[82:85], v[190:193], v[218:221], v[82:85]
	v_mfma_f32_16x16x32_bf16 v[78:81], v[182:185], v[226:229], v[78:81]
	v_mfma_f32_16x16x32_bf16 v[74:77], v[190:193], v[226:229], v[74:77]
	v_mfma_f32_16x16x32_bf16 v[66:69], v[182:185], v[240:243], v[66:69]
	v_mfma_f32_16x16x32_bf16 v[58:61], v[190:193], v[240:243], v[58:61]
	s_barrier
	s_setprio 0
	s_add_i32 s16, s16, s59
	v_lshl_add_u64 v[116:117], s[80:81], 0, v[158:159]
	s_mov_b32 m0, s16
	ds_read_b128 v[194:197], v153 offset:16384
	ds_read_b128 v[210:213], v153 offset:17408
	ds_read_b128 v[214:217], v153 offset:18432
	ds_read_b128 v[218:221], v153 offset:19456
	ds_read_b128 v[222:225], v153 offset:20480
	ds_read_b128 v[226:229], v153 offset:21504
	ds_read_b128 v[236:239], v153 offset:22528
	ds_read_b128 v[240:243], v153 offset:23552
	global_load_lds_dwordx4 v[116:117], off
	s_add_i32 m0, s16, 0x2000
	s_add_u32 s16, s80, 0x4000
	v_lshl_add_u64 v[116:117], s[80:81], 0, v[162:163]
	s_addc_u32 s17, s81, 0
	s_add_i32 s18, s18, s59
	global_load_lds_dwordx4 v[116:117], off
	v_lshl_add_u64 v[116:117], s[16:17], 0, v[158:159]
	s_mov_b32 m0, s18
	s_nop 0
	global_load_lds_dwordx4 v[116:117], off
	v_lshl_add_u64 v[116:117], s[16:17], 0, v[162:163]
	s_add_i32 m0, s18, 0x2000
	s_nop 0
	global_load_lds_dwordx4 v[116:117], off
	v_lshl_add_u64 v[116:117], s[82:83], 0, v[156:157]
	s_mov_b32 m0, s23
	s_nop 0
	global_load_lds_dwordx4 v[116:117], off
	v_lshl_add_u64 v[116:117], s[82:83], 0, v[160:161]
	s_mov_b32 m0, s25
	s_nop 0
	global_load_lds_dwordx4 v[116:117], off
	s_waitcnt vmcnt(8)
	s_waitcnt lgkmcnt(0)
	s_setprio 1
	s_barrier
	v_mfma_f32_16x16x32_bf16 v[70:73], v[136:139], v[194:197], v[70:73]
	v_mfma_f32_16x16x32_bf16 v[62:65], v[170:173], v[194:197], v[62:65]
	v_mfma_f32_16x16x32_bf16 v[54:57], v[136:139], v[214:217], v[54:57]
	v_mfma_f32_16x16x32_bf16 v[50:53], v[170:173], v[214:217], v[50:53]
	v_mfma_f32_16x16x32_bf16 v[46:49], v[136:139], v[222:225], v[46:49]
	v_mfma_f32_16x16x32_bf16 v[42:45], v[170:173], v[222:225], v[42:45]
	v_mfma_f32_16x16x32_bf16 v[38:41], v[136:139], v[236:239], v[38:41]
	v_mfma_f32_16x16x32_bf16 v[34:37], v[170:173], v[236:239], v[34:37]
	v_mfma_f32_16x16x32_bf16 v[70:73], v[140:143], v[210:213], v[70:73]
	v_mfma_f32_16x16x32_bf16 v[62:65], v[174:177], v[210:213], v[62:65]
	v_mfma_f32_16x16x32_bf16 v[54:57], v[140:143], v[218:221], v[54:57]
	v_mfma_f32_16x16x32_bf16 v[50:53], v[174:177], v[218:221], v[50:53]
	v_mfma_f32_16x16x32_bf16 v[46:49], v[140:143], v[226:229], v[46:49]
	v_mfma_f32_16x16x32_bf16 v[42:45], v[174:177], v[226:229], v[42:45]
	v_mfma_f32_16x16x32_bf16 v[38:41], v[140:143], v[240:243], v[38:41]
	v_mfma_f32_16x16x32_bf16 v[34:37], v[174:177], v[240:243], v[34:37]
	v_mfma_f32_16x16x32_bf16 v[30:33], v[178:181], v[194:197], v[30:33]
	v_mfma_f32_16x16x32_bf16 v[26:29], v[186:189], v[194:197], v[26:29]
	v_mfma_f32_16x16x32_bf16 v[22:25], v[178:181], v[214:217], v[22:25]
	v_mfma_f32_16x16x32_bf16 v[18:21], v[186:189], v[214:217], v[18:21]
	v_mfma_f32_16x16x32_bf16 v[14:17], v[178:181], v[222:225], v[14:17]
	v_mfma_f32_16x16x32_bf16 v[10:13], v[186:189], v[222:225], v[10:13]
	v_mfma_f32_16x16x32_bf16 v[6:9], v[178:181], v[236:239], v[6:9]
	v_mfma_f32_16x16x32_bf16 v[2:5], v[186:189], v[236:239], v[2:5]
	v_mfma_f32_16x16x32_bf16 v[30:33], v[182:185], v[210:213], v[30:33]
	v_mfma_f32_16x16x32_bf16 v[26:29], v[190:193], v[210:213], v[26:29]
	v_mfma_f32_16x16x32_bf16 v[22:25], v[182:185], v[218:221], v[22:25]
	v_mfma_f32_16x16x32_bf16 v[18:21], v[190:193], v[218:221], v[18:21]
	v_mfma_f32_16x16x32_bf16 v[14:17], v[182:185], v[226:229], v[14:17]
	v_mfma_f32_16x16x32_bf16 v[10:13], v[190:193], v[226:229], v[10:13]
	v_mfma_f32_16x16x32_bf16 v[6:9], v[182:185], v[240:243], v[6:9]
	v_mfma_f32_16x16x32_bf16 v[2:5], v[190:193], v[240:243], v[2:5]
	s_barrier
	s_setprio 0
	s_add_i32 s18, 0, 0x18000
	v_add_u32_e32 v114, s18, v119
	s_add_i32 s19, 0, 0x1c000
	ds_read_b128 v[136:139], v114
	ds_read_b128 v[140:143], v114 offset:1024
	ds_read_b128 v[170:173], v114 offset:2048
	ds_read_b128 v[174:177], v114 offset:3072
	v_add_u32_e32 v114, s19, v119
	ds_read_b128 v[178:181], v114
	ds_read_b128 v[182:185], v114 offset:1024
	ds_read_b128 v[186:189], v114 offset:2048
	ds_read_b128 v[190:193], v114 offset:3072
	s_add_u32 s16, s82, 0x4000
	s_addc_u32 s17, s83, 0
	s_mov_b32 m0, s42
	v_lshl_add_u64 v[116:117], s[16:17], 0, v[156:157]
	ds_read_b128 v[194:197], v153 offset:32768
	ds_read_b128 v[210:213], v153 offset:33792
	ds_read_b128 v[214:217], v153 offset:34816
	ds_read_b128 v[218:221], v153 offset:35840
	ds_read_b128 v[222:225], v153 offset:36864
	ds_read_b128 v[226:229], v153 offset:37888
	ds_read_b128 v[236:239], v153 offset:38912
	ds_read_b128 v[240:243], v153 offset:39936
	global_load_lds_dwordx4 v[116:117], off
	v_lshl_add_u64 v[116:117], s[16:17], 0, v[160:161]
	s_mov_b32 m0, s43
	s_nop 0
	global_load_lds_dwordx4 v[116:117], off
	s_waitcnt vmcnt(8)
	s_waitcnt lgkmcnt(0)
	s_setprio 1
	s_barrier
	v_mfma_f32_16x16x32_bf16 v[132:135], v[136:139], v[194:197], v[132:135]
	v_mfma_f32_16x16x32_bf16 v[128:131], v[170:173], v[194:197], v[128:131]
	v_mfma_f32_16x16x32_bf16 v[124:127], v[136:139], v[214:217], v[124:127]
	v_mfma_f32_16x16x32_bf16 v[120:123], v[170:173], v[214:217], v[120:123]
	v_mfma_f32_16x16x32_bf16 v[110:113], v[136:139], v[222:225], v[110:113]
	v_mfma_f32_16x16x32_bf16 v[106:109], v[170:173], v[222:225], v[106:109]
	v_mfma_f32_16x16x32_bf16 v[102:105], v[136:139], v[236:239], v[102:105]
	v_mfma_f32_16x16x32_bf16 v[98:101], v[170:173], v[236:239], v[98:101]
	v_mfma_f32_16x16x32_bf16 v[132:135], v[140:143], v[210:213], v[132:135]
	v_mfma_f32_16x16x32_bf16 v[128:131], v[174:177], v[210:213], v[128:131]
	v_mfma_f32_16x16x32_bf16 v[124:127], v[140:143], v[218:221], v[124:127]
	v_mfma_f32_16x16x32_bf16 v[120:123], v[174:177], v[218:221], v[120:123]
	v_mfma_f32_16x16x32_bf16 v[110:113], v[140:143], v[226:229], v[110:113]
	v_mfma_f32_16x16x32_bf16 v[106:109], v[174:177], v[226:229], v[106:109]
	v_mfma_f32_16x16x32_bf16 v[102:105], v[140:143], v[240:243], v[102:105]
	v_mfma_f32_16x16x32_bf16 v[98:101], v[174:177], v[240:243], v[98:101]
	v_mfma_f32_16x16x32_bf16 v[94:97], v[178:181], v[194:197], v[94:97]
	v_mfma_f32_16x16x32_bf16 v[90:93], v[186:189], v[194:197], v[90:93]
	v_mfma_f32_16x16x32_bf16 v[86:89], v[178:181], v[214:217], v[86:89]
	v_mfma_f32_16x16x32_bf16 v[82:85], v[186:189], v[214:217], v[82:85]
	v_mfma_f32_16x16x32_bf16 v[78:81], v[178:181], v[222:225], v[78:81]
	v_mfma_f32_16x16x32_bf16 v[74:77], v[186:189], v[222:225], v[74:77]
	v_mfma_f32_16x16x32_bf16 v[66:69], v[178:181], v[236:239], v[66:69]
	v_mfma_f32_16x16x32_bf16 v[58:61], v[186:189], v[236:239], v[58:61]
	v_mfma_f32_16x16x32_bf16 v[94:97], v[182:185], v[210:213], v[94:97]
	v_mfma_f32_16x16x32_bf16 v[90:93], v[190:193], v[210:213], v[90:93]
	v_mfma_f32_16x16x32_bf16 v[86:89], v[182:185], v[218:221], v[86:89]
	v_mfma_f32_16x16x32_bf16 v[82:85], v[190:193], v[218:221], v[82:85]
	v_mfma_f32_16x16x32_bf16 v[78:81], v[182:185], v[226:229], v[78:81]
	v_mfma_f32_16x16x32_bf16 v[74:77], v[190:193], v[226:229], v[74:77]
	v_mfma_f32_16x16x32_bf16 v[66:69], v[182:185], v[240:243], v[66:69]
	v_mfma_f32_16x16x32_bf16 v[58:61], v[190:193], v[240:243], v[58:61]
	s_barrier
	s_setprio 0
	s_add_u32 s16, s80, 0x8000
	s_addc_u32 s17, s81, 0
	s_add_i32 s18, s18, s59
	v_lshl_add_u64 v[116:117], s[16:17], 0, v[158:159]
	s_mov_b32 m0, s18
	ds_read_b128 v[194:197], v153 offset:49152
	ds_read_b128 v[210:213], v153 offset:50176
	ds_read_b128 v[214:217], v153 offset:51200
	ds_read_b128 v[218:221], v153 offset:52224
	ds_read_b128 v[222:225], v153 offset:53248
	ds_read_b128 v[226:229], v153 offset:54272
	ds_read_b128 v[236:239], v153 offset:55296
	ds_read_b128 v[240:243], v153 offset:56320
	global_load_lds_dwordx4 v[116:117], off
	s_add_i32 m0, s18, 0x2000
	v_lshl_add_u64 v[116:117], s[16:17], 0, v[162:163]
	s_add_u32 s16, s80, 0xc000
	s_addc_u32 s17, s81, 0
	s_add_i32 s18, s19, s59
	global_load_lds_dwordx4 v[116:117], off
	v_lshl_add_u64 v[116:117], s[16:17], 0, v[158:159]
	s_mov_b32 m0, s18
	s_nop 0
	global_load_lds_dwordx4 v[116:117], off
	v_lshl_add_u64 v[116:117], s[16:17], 0, v[162:163]
	s_add_i32 m0, s18, 0x2000
	s_nop 0
	global_load_lds_dwordx4 v[116:117], off
	v_lshl_add_u64 v[116:117], s[78:79], 0, v[156:157]
	s_mov_b32 m0, s53
	s_nop 0
	global_load_lds_dwordx4 v[116:117], off
	v_lshl_add_u64 v[116:117], s[78:79], 0, v[160:161]
	s_mov_b32 m0, s52
	s_nop 0
	global_load_lds_dwordx4 v[116:117], off
	s_waitcnt vmcnt(8)
	s_waitcnt lgkmcnt(0)
	s_setprio 1
	s_barrier
	v_mfma_f32_16x16x32_bf16 v[70:73], v[136:139], v[194:197], v[70:73]
	v_mfma_f32_16x16x32_bf16 v[62:65], v[170:173], v[194:197], v[62:65]
	v_mfma_f32_16x16x32_bf16 v[54:57], v[136:139], v[214:217], v[54:57]
	v_mfma_f32_16x16x32_bf16 v[50:53], v[170:173], v[214:217], v[50:53]
	v_mfma_f32_16x16x32_bf16 v[46:49], v[136:139], v[222:225], v[46:49]
	v_mfma_f32_16x16x32_bf16 v[42:45], v[170:173], v[222:225], v[42:45]
	v_mfma_f32_16x16x32_bf16 v[38:41], v[136:139], v[236:239], v[38:41]
	v_mfma_f32_16x16x32_bf16 v[34:37], v[170:173], v[236:239], v[34:37]
	v_mfma_f32_16x16x32_bf16 v[70:73], v[140:143], v[210:213], v[70:73]
	v_mfma_f32_16x16x32_bf16 v[62:65], v[174:177], v[210:213], v[62:65]
	v_mfma_f32_16x16x32_bf16 v[54:57], v[140:143], v[218:221], v[54:57]
	v_mfma_f32_16x16x32_bf16 v[50:53], v[174:177], v[218:221], v[50:53]
	v_mfma_f32_16x16x32_bf16 v[46:49], v[140:143], v[226:229], v[46:49]
	v_mfma_f32_16x16x32_bf16 v[42:45], v[174:177], v[226:229], v[42:45]
	v_mfma_f32_16x16x32_bf16 v[38:41], v[140:143], v[240:243], v[38:41]
	v_mfma_f32_16x16x32_bf16 v[34:37], v[174:177], v[240:243], v[34:37]
	v_mfma_f32_16x16x32_bf16 v[30:33], v[178:181], v[194:197], v[30:33]
	v_mfma_f32_16x16x32_bf16 v[26:29], v[186:189], v[194:197], v[26:29]
	v_mfma_f32_16x16x32_bf16 v[22:25], v[178:181], v[214:217], v[22:25]
	v_mfma_f32_16x16x32_bf16 v[18:21], v[186:189], v[214:217], v[18:21]
	v_mfma_f32_16x16x32_bf16 v[14:17], v[178:181], v[222:225], v[14:17]
	v_mfma_f32_16x16x32_bf16 v[10:13], v[186:189], v[222:225], v[10:13]
	v_mfma_f32_16x16x32_bf16 v[6:9], v[178:181], v[236:239], v[6:9]
	v_mfma_f32_16x16x32_bf16 v[2:5], v[186:189], v[236:239], v[2:5]
	v_mfma_f32_16x16x32_bf16 v[30:33], v[182:185], v[210:213], v[30:33]
	v_mfma_f32_16x16x32_bf16 v[26:29], v[190:193], v[210:213], v[26:29]
	v_mfma_f32_16x16x32_bf16 v[22:25], v[182:185], v[218:221], v[22:25]
	v_mfma_f32_16x16x32_bf16 v[18:21], v[190:193], v[218:221], v[18:21]
	v_mfma_f32_16x16x32_bf16 v[14:17], v[182:185], v[226:229], v[14:17]
	v_mfma_f32_16x16x32_bf16 v[10:13], v[190:193], v[226:229], v[10:13]
	v_mfma_f32_16x16x32_bf16 v[6:9], v[182:185], v[240:243], v[6:9]
	v_mfma_f32_16x16x32_bf16 v[2:5], v[190:193], v[240:243], v[2:5]
	s_barrier
	s_setprio 0
	s_add_u32 s40, s40, 0x10000
	s_addc_u32 s41, s41, 0
	s_add_u32 s13, s13, 0x10000
	s_addc_u32 s14, s14, 0
	s_cmp_ge_i32 s15, s68
	s_mov_b32 s16, s15
	s_cbranch_scc0 .LBB0_1372
